# hand-written attention block steps (SEL/WIN interior+edge, unitB edge): V-fragment prefetch, in-place accumulators, batched bias lookups
# speedup vs baseline: 1.0346x; 1.0346x over previous
; __device__ __forceinline__ int swz(int R) { return (R & 2) | ((R & 8) >> 1); }
; __device__ __forceinline__ void load_kfrags(bf16x8 (&kf)[4][2], const unsigned char* Ks, int r, int fq) {
; #pragma unroll
;     for (int f = 0; f < 4; ++f)
; #pragma unroll
;         for (int dc = 0; dc < 2; ++dc) { const int R = prow(f, r); kf[f][dc] = *(const bf16x8*)(Ks + R * 128 + (((4 * dc + fq) ^ swz(R)) << 4)); }
; }
; template <bool SEL> ...
;     ...
;         for (int it = it0; it < it0 + 2 && it < n; ++it) {
;             const int j = jhi - it, slot = it & 3;
;             bool selq[2] = {true, true}; bool any[2] = {true, true};
;             if (SEL) {
; #pragma unroll
;                 for (int cg_ = 0; cg_ < 2; ++cg_) {
;                     const unsigned long long wsel = j < 64 ? sw[cg_][0] : sw[cg_][1];
;                     selq[cg_] = ((wsel >> (j & 63)) & 1ull) != 0ull; any[cg_] = __any(selq[cg_]) != 0;
;                 }
;             }
;             if (any[0] || any[1]) {
;                 const unsigned char* Ks = lds + OFF_RING + slot * SLOTB; const unsigned char* Vs = Ks + 8192;
;                 bf16x8 kf[4][2]; load_kfrags(kf, Ks, r, fq);
;                 const bool edge = (j >= T - 2) || (wl == 512 && j == T - 8);
;                 if (edge) {
;                     if (any[0] && any[1]) step_edge<3>(kf, q, tq, j * 64, fq, H, btab, wl, selq, m, l, o, Vs, r);
;                     else if (any[0]) step_edge<1>(kf, q, tq, j * 64, fq, H, btab, wl, selq, m, l, o, Vs, r);
;                     else step_edge<2>(kf, q, tq, j * 64, fq, H, btab, wl, selq, m, l, o, Vs, r);
;                 } else {
;                     if (any[0] && any[1]) step_int<3>(kf, q, farb, selq, m, l, o, Vs, r, fq);
;                     else if (any[0]) step_int<1>(kf, q, farb, selq, m, l, o, Vs, r, fq);
;                     else step_int<2>(kf, q, farb, selq, m, l, o, Vs, r, fq);
;                 }
.LBB0_2146:
	v_add_u32_e32 v143, 0, v0
	v_add_u32_e32 v142, 0, v138
	s_waitcnt lgkmcnt(7)
	ds_read_b128 v[78:81], v143
	s_waitcnt lgkmcnt(7)
	ds_read_b128 v[70:73], v143 offset:512
	s_waitcnt lgkmcnt(7)
	ds_read_b128 v[74:77], v142
	s_waitcnt lgkmcnt(7)
	ds_read_b128 v[66:69], v142 offset:512
	s_waitcnt lgkmcnt(7)
	ds_read_b128 v[62:65], v143 offset:4096
	s_waitcnt lgkmcnt(7)
	ds_read_b128 v[50:53], v143 offset:4608
	s_waitcnt lgkmcnt(7)
	ds_read_b128 v[58:61], v142 offset:4096
	s_waitcnt lgkmcnt(7)
	ds_read_b128 v[54:57], v142 offset:4608
	s_cmp_lt_i32 s35, s4
	s_mov_b64 s[8:9], -1
	s_cbranch_scc1 .LBB0_2214
	s_branch .Lub_edge
	s_waitcnt lgkmcnt(7)
	v_mfma_f32_16x16x32_bf16 v[82:85], v[78:81], v[2:5], 0
	v_cmp_gt_u32_e32 vcc, s33, v140
	v_mov_b32_e32 v144, 0xf149f2ca
	v_add_u32_e32 v99, 0, v141
	s_waitcnt lgkmcnt(5)
	v_mfma_f32_16x16x32_bf16 v[94:97], v[74:77], v[6:9], v[82:85]
	v_mov_b32_e32 v145, 0xf149f2ca
	v_mfma_f32_16x16x32_bf16 v[82:85], v[70:73], v[2:5], 0
	s_waitcnt lgkmcnt(4)
	v_mfma_f32_16x16x32_bf16 v[90:93], v[66:69], v[6:9], v[82:85]
	s_waitcnt lgkmcnt(3)
	v_mfma_f32_16x16x32_bf16 v[82:85], v[62:65], v[2:5], 0
	s_waitcnt lgkmcnt(1)
	v_mfma_f32_16x16x32_bf16 v[86:89], v[58:61], v[6:9], v[82:85]
	v_mfma_f32_16x16x32_bf16 v[82:85], v[50:53], v[2:5], 0
	s_waitcnt lgkmcnt(0)
	v_mfma_f32_16x16x32_bf16 v[82:85], v[54:57], v[6:9], v[82:85]
	s_and_saveexec_b64 s[8:9], vcc
	s_cbranch_execz .LBB0_2149
	ds_read_b32 v98, v99
	s_waitcnt lgkmcnt(0)
	v_add_f32_e32 v145, v94, v98

; __device__ __forceinline__ void logits(float (&v)[4][4], const f32x4 (&s)[4], int tq, int kpos0, int kstride, int fq, int H, const float* btab, float farb, bool use_tab, int wl) {
; #pragma unroll
;     for (int f = 0; f < 4; ++f)
; #pragma unroll
;         for (int i = 0; i < 4; ++i) {
;             const int kk = 32 * (f >> 1) + 8 * fq + 4 * (f & 1) + i;
;             const int dist = tq - (kpos0 + kstride * kk);
;             const bool ok = dist >= 0 && dist < wl;
;             const int di = dist < 0 ? 0 : (dist > 128 ? 128 : dist);
;             v[f][i] = ok ? s[f][i] + btab[di * 16 + H] : -1e30f;
;         }
; }
; template <int CGM> ...
;     float v[2][4][4]; float mnew[2] = {m[0], m[1]};
; #pragma unroll
;     for (int cg_ = 0; cg_ < 2; ++cg_) if ((CGM >> cg_) & 1) {
;         f32x4 s[4]; qk(s, kf, q[cg_], 0.f); logits(v[cg_], s, tq[cg_], key0, 1, fq, H, btab, 0.f, true, wl);
;         float mx = red_max4(max16(v[cg_])); if (!selq[cg_]) mx = -1e30f; mnew[cg_] = fmaxf(m[cg_], mx);
;     }
.Lub_edge:
	s_waitcnt lgkmcnt(7)
	v_mfma_f32_16x16x32_bf16 v[150:153], v[78:81], v[2:5], 0
	v_mfma_f32_16x16x32_bf16 v[158:161], v[78:81], v[10:13], 0
	s_waitcnt lgkmcnt(6)
	v_mfma_f32_16x16x32_bf16 v[154:157], v[70:73], v[2:5], 0
	v_mfma_f32_16x16x32_bf16 v[174:177], v[70:73], v[10:13], 0
	s_waitcnt lgkmcnt(5)
	v_mfma_f32_16x16x32_bf16 v[150:153], v[74:77], v[6:9], v[150:153]
	v_mfma_f32_16x16x32_bf16 v[158:161], v[74:77], v[14:17], v[158:161]
	s_waitcnt lgkmcnt(4)
	v_mfma_f32_16x16x32_bf16 v[154:157], v[66:69], v[6:9], v[154:157]
	v_mfma_f32_16x16x32_bf16 v[174:177], v[66:69], v[14:17], v[174:177]
	s_waitcnt lgkmcnt(3)
	v_mfma_f32_16x16x32_bf16 v[98:101], v[62:65], v[2:5], 0
	v_mfma_f32_16x16x32_bf16 v[106:109], v[62:65], v[10:13], 0
	s_waitcnt lgkmcnt(2)
	v_mfma_f32_16x16x32_bf16 v[102:105], v[50:53], v[2:5], 0
	v_mfma_f32_16x16x32_bf16 v[110:113], v[50:53], v[10:13], 0
	s_waitcnt lgkmcnt(1)
	v_mfma_f32_16x16x32_bf16 v[98:101], v[58:61], v[6:9], v[98:101]
	v_mfma_f32_16x16x32_bf16 v[106:109], v[58:61], v[14:17], v[106:109]
	s_waitcnt lgkmcnt(0)
	v_mfma_f32_16x16x32_bf16 v[102:105], v[54:57], v[6:9], v[102:105]
	v_mfma_f32_16x16x32_bf16 v[110:113], v[54:57], v[14:17], v[110:113]
	v_add_u32_e32 v255, 0, v140
	v_min_u32_e32 v255, 0x80, v255
	v_lshl_add_u32 v232, v255, 6, v137
	ds_read_b32 v232, v232
	v_add_u32_e32 v255, -1, v140
	v_min_u32_e32 v255, 0x80, v255
	v_lshl_add_u32 v233, v255, 6, v137
	ds_read_b32 v233, v233
	v_add_u32_e32 v255, -2, v140
	v_min_u32_e32 v255, 0x80, v255
	v_lshl_add_u32 v234, v255, 6, v137
	ds_read_b32 v234, v234
	v_add_u32_e32 v255, -3, v140
	v_min_u32_e32 v255, 0x80, v255
	v_lshl_add_u32 v235, v255, 6, v137
	ds_read_b32 v235, v235
	v_add_u32_e32 v255, -4, v140
	v_min_u32_e32 v255, 0x80, v255
	v_lshl_add_u32 v236, v255, 6, v137
	ds_read_b32 v236, v236
	v_add_u32_e32 v255, -5, v140
	v_min_u32_e32 v255, 0x80, v255
	v_lshl_add_u32 v237, v255, 6, v137
	ds_read_b32 v237, v237
	v_add_u32_e32 v255, -6, v140
	v_min_u32_e32 v255, 0x80, v255
	v_lshl_add_u32 v238, v255, 6, v137
	ds_read_b32 v238, v238
	v_add_u32_e32 v255, -7, v140
	v_min_u32_e32 v255, 0x80, v255
	v_lshl_add_u32 v239, v255, 6, v137
	ds_read_b32 v239, v239
	v_add_u32_e32 v255, 0xffffffe0, v140
	v_min_u32_e32 v255, 0x80, v255
	v_lshl_add_u32 v240, v255, 6, v137
	ds_read_b32 v240, v240
	v_add_u32_e32 v255, 0xffffffdf, v140
	v_min_u32_e32 v255, 0x80, v255
	v_lshl_add_u32 v241, v255, 6, v137
	ds_read_b32 v241, v241
	v_add_u32_e32 v255, 0xffffffde, v140
	v_min_u32_e32 v255, 0x80, v255
	v_lshl_add_u32 v242, v255, 6, v137
	ds_read_b32 v242, v242
	v_add_u32_e32 v255, 0xffffffdd, v140
	v_min_u32_e32 v255, 0x80, v255
	v_lshl_add_u32 v243, v255, 6, v137
	ds_read_b32 v243, v243
	v_add_u32_e32 v255, 0xffffffdc, v140
	v_min_u32_e32 v255, 0x80, v255
	v_lshl_add_u32 v244, v255, 6, v137
	ds_read_b32 v244, v244
	v_add_u32_e32 v255, 0xffffffdb, v140
	v_min_u32_e32 v255, 0x80, v255
	v_lshl_add_u32 v245, v255, 6, v137
	ds_read_b32 v245, v245
	v_add_u32_e32 v255, 0xffffffda, v140
	v_min_u32_e32 v255, 0x80, v255
	v_lshl_add_u32 v246, v255, 6, v137
	ds_read_b32 v246, v246
	v_add_u32_e32 v255, 0xffffffd9, v140
	v_min_u32_e32 v255, 0x80, v255
	v_lshl_add_u32 v247, v255, 6, v137
	ds_read_b32 v247, v247
	v_add_u32_e32 v248, 0, v140
	v_cmp_gt_u32_e64 s[8:9], s33, v248
	v_add_u32_e32 v249, -1, v140
	v_cmp_gt_u32_e64 s[10:11], s33, v249
	v_add_u32_e32 v250, -2, v140
	v_cmp_gt_u32_e64 s[12:13], s33, v250
	s_waitcnt lgkmcnt(15)
	v_add_f32_e32 v150, v150, v232
	v_cndmask_b32_e64 v150, v148, v150, s[8:9]
	v_add_u32_e32 v248, -3, v140
	v_cmp_gt_u32_e64 s[8:9], s33, v248
	s_waitcnt lgkmcnt(14)
	v_add_f32_e32 v151, v151, v233
	v_cndmask_b32_e64 v151, v148, v151, s[10:11]
	v_add_u32_e32 v249, -4, v140
	v_cmp_gt_u32_e64 s[10:11], s33, v249
	s_waitcnt lgkmcnt(13)
	v_add_f32_e32 v152, v152, v234
	v_cndmask_b32_e64 v152, v148, v152, s[12:13]
	v_add_u32_e32 v250, -5, v140
	v_cmp_gt_u32_e64 s[12:13], s33, v250
	s_waitcnt lgkmcnt(12)
	v_add_f32_e32 v153, v153, v235
	v_cndmask_b32_e64 v153, v148, v153, s[8:9]
	v_add_u32_e32 v248, -6, v140
	v_cmp_gt_u32_e64 s[8:9], s33, v248
	s_waitcnt lgkmcnt(11)
	v_add_f32_e32 v154, v154, v236
	v_cndmask_b32_e64 v154, v148, v154, s[10:11]
	v_add_u32_e32 v249, -7, v140
	v_cmp_gt_u32_e64 s[10:11], s33, v249
	s_waitcnt lgkmcnt(10)
	v_add_f32_e32 v155, v155, v237
	v_cndmask_b32_e64 v155, v148, v155, s[12:13]
	v_add_u32_e32 v250, 0xffffffe0, v140
	v_cmp_gt_u32_e64 s[12:13], s33, v250
	s_waitcnt lgkmcnt(9)
	v_add_f32_e32 v156, v156, v238
	v_cndmask_b32_e64 v156, v148, v156, s[8:9]
	v_add_u32_e32 v248, 0xffffffdf, v140
	v_cmp_gt_u32_e64 s[8:9], s33, v248
	s_waitcnt lgkmcnt(8)
	v_add_f32_e32 v157, v157, v239
	v_cndmask_b32_e64 v157, v148, v157, s[10:11]
	v_add_u32_e32 v249, 0xffffffde, v140
	v_cmp_gt_u32_e64 s[10:11], s33, v249
	s_waitcnt lgkmcnt(7)
	v_add_f32_e32 v98, v98, v240
	v_cndmask_b32_e64 v98, v148, v98, s[12:13]
	v_add_u32_e32 v250, 0xffffffdd, v140
	v_cmp_gt_u32_e64 s[12:13], s33, v250
	s_waitcnt lgkmcnt(6)
	v_add_f32_e32 v99, v99, v241
	v_cndmask_b32_e64 v99, v148, v99, s[8:9]
	v_add_u32_e32 v248, 0xffffffdc, v140
	v_cmp_gt_u32_e64 s[8:9], s33, v248
	s_waitcnt lgkmcnt(5)
	v_add_f32_e32 v100, v100, v242
	v_cndmask_b32_e64 v100, v148, v100, s[10:11]
	v_add_u32_e32 v249, 0xffffffdb, v140
	v_cmp_gt_u32_e64 s[10:11], s33, v249
	s_waitcnt lgkmcnt(4)
	v_add_f32_e32 v101, v101, v243
	v_cndmask_b32_e64 v101, v148, v101, s[12:13]
	v_add_u32_e32 v250, 0xffffffda, v140
	v_cmp_gt_u32_e64 s[12:13], s33, v250
	s_waitcnt lgkmcnt(3)
	v_add_f32_e32 v102, v102, v244
	v_cndmask_b32_e64 v102, v148, v102, s[8:9]
	v_add_u32_e32 v248, 0xffffffd9, v140
	v_cmp_gt_u32_e64 s[8:9], s33, v248
	s_waitcnt lgkmcnt(2)
; __device__ __forceinline__ void logits(float (&v)[4][4], const f32x4 (&s)[4], int tq, int kpos0, int kstride, int fq, int H, const float* btab, float farb, bool use_tab, int wl) {
; #pragma unroll
;     for (int f = 0; f < 4; ++f)
; #pragma unroll
;         for (int i = 0; i < 4; ++i) {
;             const int kk = 32 * (f >> 1) + 8 * fq + 4 * (f & 1) + i;
;             const int dist = tq - (kpos0 + kstride * kk);
;             const bool ok = dist >= 0 && dist < wl;
;             const int di = dist < 0 ? 0 : (dist > 128 ? 128 : dist);
;             v[f][i] = ok ? s[f][i] + btab[di * 16 + H] : -1e30f;
;         }
; }
; __device__ __forceinline__ float red_max4(float x) {
;     auto a = __builtin_amdgcn_permlane16_swap(__float_as_uint(x), __float_as_uint(x), false, false); x = fmaxf(__uint_as_float(a[0]), __uint_as_float(a[1]));
;     auto b = __builtin_amdgcn_permlane32_swap(__float_as_uint(x), __float_as_uint(x), false, false); return fmaxf(__uint_as_float(b[0]), __uint_as_float(b[1]));
; }
; __device__ __forceinline__ float quad_sum(float x) {
;     auto a = __builtin_amdgcn_permlane16_swap(__float_as_uint(x), __float_as_uint(x), false, false); x = __uint_as_float(a[0]) + __uint_as_float(a[1]);
;     auto b = __builtin_amdgcn_permlane32_swap(__float_as_uint(x), __float_as_uint(x), false, false); return __uint_as_float(b[0]) + __uint_as_float(b[1]);
; }
; __device__ __forceinline__ float dpp_xor1(float x) { return __builtin_bit_cast(float, __builtin_amdgcn_update_dpp(0, __builtin_bit_cast(int, x), 0xB1, 0xF, 0xF, true)); }
; __device__ __forceinline__ float dpp_xor2(float x) { return __builtin_bit_cast(float, __builtin_amdgcn_update_dpp(0, __builtin_bit_cast(int, x), 0x4E, 0xF, 0xF, true)); }
; __device__ __forceinline__ float max16(const float (&v)[4][4]) {
;     float a = fmaxf(fmaxf(v[0][0], v[0][1]), fmaxf(v[0][2], v[0][3])), b = fmaxf(fmaxf(v[1][0], v[1][1]), fmaxf(v[1][2], v[1][3]));
;     float c = fmaxf(fmaxf(v[2][0], v[2][1]), fmaxf(v[2][2], v[2][3])), d = fmaxf(fmaxf(v[3][0], v[3][1]), fmaxf(v[3][2], v[3][3]));
;     return fmaxf(fmaxf(a, b), fmaxf(c, d));
; }
; __device__ __forceinline__ float max3f(float a, float b, float c) { float r; asm("v_max3_f32 %0, %1, %2, %3" : "=v"(r) : "v"(a), "v"(b), "v"(c)); return r; }
; __device__ __forceinline__ float max16v(const f32x4 (&s)[4]) {
	v_add_f32_e32 v103, v103, v245
	v_cndmask_b32_e64 v103, v148, v103, s[10:11]
	s_waitcnt lgkmcnt(1)
	v_add_f32_e32 v104, v104, v246
	v_cndmask_b32_e64 v104, v148, v104, s[12:13]
	s_waitcnt lgkmcnt(0)
	v_add_f32_e32 v105, v105, v247
	v_cndmask_b32_e64 v105, v148, v105, s[8:9]
	v_add_u32_e32 v255, 4, v140
	v_min_u32_e32 v255, 0x80, v255
	v_lshl_add_u32 v232, v255, 6, v137
	ds_read_b32 v232, v232
	v_add_u32_e32 v255, 3, v140
	v_min_u32_e32 v255, 0x80, v255
	v_lshl_add_u32 v233, v255, 6, v137
	ds_read_b32 v233, v233
	v_add_u32_e32 v255, 2, v140
	v_min_u32_e32 v255, 0x80, v255
	v_lshl_add_u32 v234, v255, 6, v137
	ds_read_b32 v234, v234
	v_add_u32_e32 v255, 1, v140
	v_min_u32_e32 v255, 0x80, v255
	v_lshl_add_u32 v235, v255, 6, v137
	ds_read_b32 v235, v235
	v_add_u32_e32 v255, 0, v140
	v_min_u32_e32 v255, 0x80, v255
	v_lshl_add_u32 v236, v255, 6, v137
	ds_read_b32 v236, v236
	v_add_u32_e32 v255, -1, v140
	v_min_u32_e32 v255, 0x80, v255
	v_lshl_add_u32 v237, v255, 6, v137
	ds_read_b32 v237, v237
	v_add_u32_e32 v255, -2, v140
	v_min_u32_e32 v255, 0x80, v255
	v_lshl_add_u32 v238, v255, 6, v137
	ds_read_b32 v238, v238
	v_add_u32_e32 v255, -3, v140
	v_min_u32_e32 v255, 0x80, v255
	v_lshl_add_u32 v239, v255, 6, v137
	ds_read_b32 v239, v239
	v_add_u32_e32 v255, 0xffffffe4, v140
	v_min_u32_e32 v255, 0x80, v255
	v_lshl_add_u32 v240, v255, 6, v137
	ds_read_b32 v240, v240
	v_add_u32_e32 v255, 0xffffffe3, v140
	v_min_u32_e32 v255, 0x80, v255
	v_lshl_add_u32 v241, v255, 6, v137
	ds_read_b32 v241, v241
	v_add_u32_e32 v255, 0xffffffe2, v140
	v_min_u32_e32 v255, 0x80, v255
	v_lshl_add_u32 v242, v255, 6, v137
	ds_read_b32 v242, v242
	v_add_u32_e32 v255, 0xffffffe1, v140
	v_min_u32_e32 v255, 0x80, v255
	v_lshl_add_u32 v243, v255, 6, v137
	ds_read_b32 v243, v243
	v_add_u32_e32 v255, 0xffffffe0, v140
	v_min_u32_e32 v255, 0x80, v255
	v_lshl_add_u32 v244, v255, 6, v137
	ds_read_b32 v244, v244
	v_add_u32_e32 v255, 0xffffffdf, v140
	v_min_u32_e32 v255, 0x80, v255
	v_lshl_add_u32 v245, v255, 6, v137
	ds_read_b32 v245, v245
	v_add_u32_e32 v255, 0xffffffde, v140
	v_min_u32_e32 v255, 0x80, v255
	v_lshl_add_u32 v246, v255, 6, v137
	ds_read_b32 v246, v246
	v_add_u32_e32 v255, 0xffffffdd, v140
	v_min_u32_e32 v255, 0x80, v255
	v_lshl_add_u32 v247, v255, 6, v137
	ds_read_b32 v247, v247
	v_add_u32_e32 v248, 4, v140
	v_cmp_gt_u32_e64 s[8:9], s33, v248
	v_add_u32_e32 v249, 3, v140
	v_cmp_gt_u32_e64 s[10:11], s33, v249
	v_add_u32_e32 v250, 2, v140
	v_cmp_gt_u32_e64 s[12:13], s33, v250
	s_waitcnt lgkmcnt(15)
	v_add_f32_e32 v158, v158, v232
	v_cndmask_b32_e64 v158, v148, v158, s[8:9]
	v_add_u32_e32 v248, 1, v140
	v_cmp_gt_u32_e64 s[8:9], s33, v248
	s_waitcnt lgkmcnt(14)
	v_add_f32_e32 v159, v159, v233
	v_cndmask_b32_e64 v159, v148, v159, s[10:11]
	v_add_u32_e32 v249, 0, v140
	v_cmp_gt_u32_e64 s[10:11], s33, v249
	s_waitcnt lgkmcnt(13)
	v_add_f32_e32 v160, v160, v234
	v_cndmask_b32_e64 v160, v148, v160, s[12:13]
	v_add_u32_e32 v250, -1, v140
	v_cmp_gt_u32_e64 s[12:13], s33, v250
	s_waitcnt lgkmcnt(12)
	v_add_f32_e32 v161, v161, v235
	v_cndmask_b32_e64 v161, v148, v161, s[8:9]
	v_add_u32_e32 v248, -2, v140
	v_cmp_gt_u32_e64 s[8:9], s33, v248
	s_waitcnt lgkmcnt(11)
	v_add_f32_e32 v174, v174, v236
	v_cndmask_b32_e64 v174, v148, v174, s[10:11]
	v_add_u32_e32 v249, -3, v140
	v_cmp_gt_u32_e64 s[10:11], s33, v249
	s_waitcnt lgkmcnt(10)
	v_add_f32_e32 v175, v175, v237
	v_cndmask_b32_e64 v175, v148, v175, s[12:13]
	v_add_u32_e32 v250, 0xffffffe4, v140
	v_cmp_gt_u32_e64 s[12:13], s33, v250
	s_waitcnt lgkmcnt(9)
	v_add_f32_e32 v176, v176, v238
	v_cndmask_b32_e64 v176, v148, v176, s[8:9]
	v_add_u32_e32 v248, 0xffffffe3, v140
	v_cmp_gt_u32_e64 s[8:9], s33, v248
	s_waitcnt lgkmcnt(8)
	v_add_f32_e32 v177, v177, v239
	v_cndmask_b32_e64 v177, v148, v177, s[10:11]
	v_add_u32_e32 v249, 0xffffffe2, v140
	v_cmp_gt_u32_e64 s[10:11], s33, v249
	s_waitcnt lgkmcnt(7)
	v_add_f32_e32 v106, v106, v240
	v_cndmask_b32_e64 v106, v148, v106, s[12:13]
	v_add_u32_e32 v250, 0xffffffe1, v140
	v_cmp_gt_u32_e64 s[12:13], s33, v250
	s_waitcnt lgkmcnt(6)
	v_add_f32_e32 v107, v107, v241
	v_cndmask_b32_e64 v107, v148, v107, s[8:9]
	v_add_u32_e32 v248, 0xffffffe0, v140
	v_cmp_gt_u32_e64 s[8:9], s33, v248
	s_waitcnt lgkmcnt(5)
	v_add_f32_e32 v108, v108, v242
	v_cndmask_b32_e64 v108, v148, v108, s[10:11]
	v_add_u32_e32 v249, 0xffffffdf, v140
	v_cmp_gt_u32_e64 s[10:11], s33, v249
	s_waitcnt lgkmcnt(4)
	v_add_f32_e32 v109, v109, v243
	v_cndmask_b32_e64 v109, v148, v109, s[12:13]
	v_add_u32_e32 v250, 0xffffffde, v140
	v_cmp_gt_u32_e64 s[12:13], s33, v250
	s_waitcnt lgkmcnt(3)
	v_add_f32_e32 v110, v110, v244
	v_cndmask_b32_e64 v110, v148, v110, s[8:9]
	v_add_u32_e32 v248, 0xffffffdd, v140
	v_cmp_gt_u32_e64 s[8:9], s33, v248
	s_waitcnt lgkmcnt(2)
	v_add_f32_e32 v111, v111, v245
	v_cndmask_b32_e64 v111, v148, v111, s[10:11]
	s_waitcnt lgkmcnt(1)
	v_add_f32_e32 v112, v112, v246
	v_cndmask_b32_e64 v112, v148, v112, s[12:13]
	s_waitcnt lgkmcnt(0)
	v_add_f32_e32 v113, v113, v247
	v_cndmask_b32_e64 v113, v148, v113, s[8:9]
	ds_read_b128 v[78:81], v143 offset:8192
	ds_read_b128 v[70:73], v143 offset:8704
	ds_read_b128 v[62:65], v143 offset:12288
	ds_read_b128 v[50:53], v143 offset:12800
	ds_read_b128 v[74:77], v142 offset:8192
	ds_read_b128 v[66:69], v142 offset:8704
	ds_read_b128 v[58:61], v142 offset:12288
	ds_read_b128 v[54:57], v142 offset:12800
	v_max3_f32 v144, v150, v151, v152
	v_max3_f32 v145, v153, v154, v155
	v_max3_f32 v146, v156, v157, v98
	v_max3_f32 v147, v99, v100, v101
	v_max3_f32 v178, v158, v159, v160
	v_max3_f32 v179, v161, v174, v175
	v_max3_f32 v180, v176, v177, v106
	v_max3_f32 v181, v107, v108, v109
	v_max3_f32 v144, v144, v102, v103
	v_max3_f32 v145, v145, v104, v105
	v_max3_f32 v178, v178, v110, v111
	v_max3_f32 v179, v179, v112, v113
	v_max3_f32 v144, v144, v145, v146
	v_max3_f32 v178, v178, v179, v180
	v_max_f32_e32 v144, v144, v147
	v_max_f32_e32 v178, v178, v181
	v_mov_b32_e32 v145, v144
	v_mov_b32_e32 v179, v178
	s_nop 1
	v_permlane16_swap_b32_e32 v144, v145
	v_permlane16_swap_b32_e32 v178, v179
	v_max_f32_e32 v144, v144, v145
	v_max_f32_e32 v178, v178, v179
	v_mov_b32_e32 v145, v144
	v_mov_b32_e32 v179, v178
	s_nop 1
	v_permlane32_swap_b32_e32 v144, v145
	v_permlane32_swap_b32_e32 v178, v179
	v_max_f32_e32 v144, v144, v145
	v_max_f32_e32 v178, v178, v179
	v_max_f32_e32 v145, v122, v144
	v_max_f32_e32 v179, v123, v178
	v_cmp_gt_f32_e32 vcc, v145, v122
	v_cmp_gt_f32_e64 s[8:9], v179, v123
	s_or_b64 vcc, vcc, s[8:9]
	s_cbranch_vccz .Lub_edge_nors
; __device__ __forceinline__ unsigned cvt_pk_bf16(float lo, float hi) { unsigned r; asm volatile("v_cvt_pk_bf16_f32 %0, %1, %2" : "=v"(r) : "v"(lo), "v"(hi)); return r; }
; __device__ __forceinline__ int swz(int R) { return (R & 2) | ((R & 8) >> 1); }
; template <int CGM>
; __device__ __forceinline__ void pv2(f32x4 (&o)[2][4], const float (&p)[2][4][4], const unsigned char* Vs, int r, int fq) {
;     bf16x8 pb[2][2];
; #pragma unroll
;     for (int cg_ = 0; cg_ < 2; ++cg_) if ((CGM >> cg_) & 1)
; #pragma unroll
;         for (int kc = 0; kc < 2; ++kc) {
;             u32x4 w; w.x = cvt_pk_bf16(p[cg_][2 * kc][0], p[cg_][2 * kc][1]); w.y = cvt_pk_bf16(p[cg_][2 * kc][2], p[cg_][2 * kc][3]);
;             w.z = cvt_pk_bf16(p[cg_][2 * kc + 1][0], p[cg_][2 * kc + 1][1]); w.w = cvt_pk_bf16(p[cg_][2 * kc + 1][2], p[cg_][2 * kc + 1][3]);
;             pb[cg_][kc] = __builtin_bit_cast(bf16x8, w);
;         }
; #pragma unroll
;     for (int df = 0; df < 4; ++df)
; #pragma unroll
;         for (int kc = 0; kc < 2; ++kc) {
;             const int R = prow(df, r);
;             const bf16x8 vf = *(const bf16x8*)(Vs + R * 128 + (((4 * kc + fq) ^ swz(R)) << 4));
;             if (CGM & 1) o[0][df] = __builtin_amdgcn_mfma_f32_16x16x32_bf16(vf, pb[0][kc], o[0][df], 0, 0, 0);
;             if (CGM & 2) o[1][df] = __builtin_amdgcn_mfma_f32_16x16x32_bf16(vf, pb[1][kc], o[1][df], 0, 0, 0);
;         }
; }
; template <int CGM> ...
;     ...
;     if (__any(mnew[0] > m[0] || mnew[1] > m[1])) {
; #pragma unroll
;         for (int cg_ = 0; cg_ < 2; ++cg_) if ((CGM >> cg_) & 1) {
;             const float sc = __builtin_amdgcn_exp2f(m[cg_] - mnew[cg_]); l[cg_] *= sc; m[cg_] = mnew[cg_];
; #pragma unroll
;             for (int df = 0; df < 4; ++df) o[cg_][df] *= sc;
;         }
;     }
; #pragma unroll
;     for (int cg_ = 0; cg_ < 2; ++cg_) if ((CGM >> cg_) & 1) {
;         const float moff = selq[cg_] ? m[cg_] : 1e30f; float rs = 0.f;
; #pragma unroll
;         for (int f = 0; f < 4; ++f)
; #pragma unroll
;             for (int i = 0; i < 4; ++i) { const float pe = __builtin_amdgcn_exp2f(v[cg_][f][i] - moff); v[cg_][f][i] = pe; rs += pe; }
;         l[cg_] += rs;
;     }
;     pv2<CGM>(o, v, Vs, r, fq);
; }
	v_sub_f32_e32 v144, v122, v145
	v_sub_f32_e32 v180, v123, v179
	v_exp_f32_e32 v144, v144
	v_exp_f32_e32 v180, v180
	v_mov_b32_e32 v122, v145
	v_mov_b32_e32 v123, v179
	v_mul_f32_e32 v124, v124, v144
	v_pk_mul_f32 v[46:47], v[46:47], v[144:145] op_sel_hi:[1,0]
	v_pk_mul_f32 v[48:49], v[48:49], v[144:145] op_sel_hi:[1,0]
	v_pk_mul_f32 v[38:39], v[38:39], v[144:145] op_sel_hi:[1,0]
	v_pk_mul_f32 v[40:41], v[40:41], v[144:145] op_sel_hi:[1,0]
	v_pk_mul_f32 v[30:31], v[30:31], v[144:145] op_sel_hi:[1,0]
	v_pk_mul_f32 v[32:33], v[32:33], v[144:145] op_sel_hi:[1,0]
	v_pk_mul_f32 v[22:23], v[22:23], v[144:145] op_sel_hi:[1,0]
	v_pk_mul_f32 v[24:25], v[24:25], v[144:145] op_sel_hi:[1,0]
	v_mul_f32_e32 v125, v125, v180
	v_pk_mul_f32 v[42:43], v[42:43], v[180:181] op_sel_hi:[1,0]
	v_pk_mul_f32 v[44:45], v[44:45], v[180:181] op_sel_hi:[1,0]
	v_pk_mul_f32 v[34:35], v[34:35], v[180:181] op_sel_hi:[1,0]
	v_pk_mul_f32 v[36:37], v[36:37], v[180:181] op_sel_hi:[1,0]
	v_pk_mul_f32 v[26:27], v[26:27], v[180:181] op_sel_hi:[1,0]
	v_pk_mul_f32 v[28:29], v[28:29], v[180:181] op_sel_hi:[1,0]
	v_pk_mul_f32 v[18:19], v[18:19], v[180:181] op_sel_hi:[1,0]
	v_pk_mul_f32 v[20:21], v[20:21], v[180:181] op_sel_hi:[1,0]
.Lub_edge_nors:
	v_mov_b32_e32 v146, v122
	v_mov_b32_e32 v181, v123
	v_sub_f32_e32 v150, v150, v146
	v_sub_f32_e32 v151, v151, v146
	v_sub_f32_e32 v152, v152, v146
	v_sub_f32_e32 v153, v153, v146
	v_sub_f32_e32 v154, v154, v146
	v_sub_f32_e32 v155, v155, v146
	v_sub_f32_e32 v156, v156, v146
	v_sub_f32_e32 v157, v157, v146
	v_sub_f32_e32 v98, v98, v146
	v_sub_f32_e32 v99, v99, v146
	v_sub_f32_e32 v100, v100, v146
	v_sub_f32_e32 v101, v101, v146
	v_sub_f32_e32 v102, v102, v146
	v_sub_f32_e32 v103, v103, v146
	v_sub_f32_e32 v104, v104, v146
	v_sub_f32_e32 v105, v105, v146
	v_sub_f32_e32 v158, v158, v181
	v_sub_f32_e32 v159, v159, v181
	v_sub_f32_e32 v160, v160, v181
	v_sub_f32_e32 v161, v161, v181
	v_sub_f32_e32 v174, v174, v181
	v_sub_f32_e32 v175, v175, v181
	v_sub_f32_e32 v176, v176, v181
	v_sub_f32_e32 v177, v177, v181
	v_sub_f32_e32 v106, v106, v181
	v_sub_f32_e32 v107, v107, v181
	v_sub_f32_e32 v108, v108, v181
	v_sub_f32_e32 v109, v109, v181
	v_sub_f32_e32 v110, v110, v181
	v_sub_f32_e32 v111, v111, v181
	v_sub_f32_e32 v112, v112, v181
	v_sub_f32_e32 v113, v113, v181
	v_exp_f32_e32 v150, v150
	v_exp_f32_e32 v151, v151
	v_exp_f32_e32 v152, v152
	v_exp_f32_e32 v153, v153
	v_exp_f32_e32 v154, v154
	v_exp_f32_e32 v155, v155
	v_exp_f32_e32 v156, v156
	v_exp_f32_e32 v157, v157
	v_exp_f32_e32 v98, v98
	v_exp_f32_e32 v99, v99
	v_exp_f32_e32 v100, v100
	v_exp_f32_e32 v101, v101
	v_exp_f32_e32 v102, v102
	v_exp_f32_e32 v103, v103
	v_exp_f32_e32 v104, v104
	v_exp_f32_e32 v105, v105
	v_exp_f32_e32 v158, v158
	v_exp_f32_e32 v159, v159
	v_exp_f32_e32 v160, v160
	v_exp_f32_e32 v161, v161
	v_exp_f32_e32 v174, v174
	v_exp_f32_e32 v175, v175
	v_exp_f32_e32 v176, v176
	v_exp_f32_e32 v177, v177
	v_exp_f32_e32 v106, v106
	v_exp_f32_e32 v107, v107
	v_exp_f32_e32 v108, v108
	v_exp_f32_e32 v109, v109
	v_exp_f32_e32 v110, v110
	v_exp_f32_e32 v111, v111
	v_exp_f32_e32 v112, v112
	v_exp_f32_e32 v113, v113
	v_pk_add_f32 v[146:147], v[150:151], v[152:153]
	v_pk_add_f32 v[146:147], v[146:147], v[154:155]
	v_pk_add_f32 v[146:147], v[146:147], v[156:157]
	v_pk_add_f32 v[146:147], v[146:147], v[98:99]
	v_pk_add_f32 v[146:147], v[146:147], v[100:101]
	v_pk_add_f32 v[146:147], v[146:147], v[102:103]
	v_pk_add_f32 v[146:147], v[146:147], v[104:105]
	v_pk_add_f32 v[180:181], v[158:159], v[160:161]
	v_pk_add_f32 v[180:181], v[180:181], v[174:175]
	v_pk_add_f32 v[180:181], v[180:181], v[176:177]
	v_pk_add_f32 v[180:181], v[180:181], v[106:107]
	v_pk_add_f32 v[180:181], v[180:181], v[108:109]
	v_pk_add_f32 v[180:181], v[180:181], v[110:111]
	v_pk_add_f32 v[180:181], v[180:181], v[112:113]
	v_add_f32_e32 v146, v146, v147
	v_add_f32_e32 v180, v180, v181
	v_add_f32_e32 v126, v124, v146
	v_add_f32_e32 v127, v125, v180
	v_cvt_pk_bf16_f32 v150, v150, v151
	v_cvt_pk_bf16_f32 v151, v152, v153
	v_cvt_pk_bf16_f32 v152, v154, v155
	v_cvt_pk_bf16_f32 v153, v156, v157
	v_cvt_pk_bf16_f32 v154, v98, v99
	v_cvt_pk_bf16_f32 v155, v100, v101
	v_cvt_pk_bf16_f32 v156, v102, v103
	v_cvt_pk_bf16_f32 v157, v104, v105
	v_cvt_pk_bf16_f32 v158, v158, v159
	v_cvt_pk_bf16_f32 v159, v160, v161
	v_cvt_pk_bf16_f32 v160, v174, v175
	v_cvt_pk_bf16_f32 v161, v176, v177
	v_cvt_pk_bf16_f32 v174, v106, v107
	v_cvt_pk_bf16_f32 v175, v108, v109
	v_cvt_pk_bf16_f32 v176, v110, v111
	v_cvt_pk_bf16_f32 v177, v112, v113
	v_mov_b64_e32 v[128:129], v[122:123]
	s_nop 0
	s_waitcnt lgkmcnt(7)
	v_mfma_f32_16x16x32_bf16 v[46:49], v[78:81], v[150:153], v[46:49]
	v_mfma_f32_16x16x32_bf16 v[42:45], v[78:81], v[158:161], v[42:45]
	s_waitcnt lgkmcnt(6)
	v_mfma_f32_16x16x32_bf16 v[38:41], v[70:73], v[150:153], v[38:41]
	v_mfma_f32_16x16x32_bf16 v[34:37], v[70:73], v[158:161], v[34:37]
	s_waitcnt lgkmcnt(5)
	v_mfma_f32_16x16x32_bf16 v[30:33], v[62:65], v[150:153], v[30:33]
	v_mfma_f32_16x16x32_bf16 v[26:29], v[62:65], v[158:161], v[26:29]
	s_waitcnt lgkmcnt(4)
	v_mfma_f32_16x16x32_bf16 v[22:25], v[50:53], v[150:153], v[22:25]
	v_mfma_f32_16x16x32_bf16 v[18:21], v[50:53], v[158:161], v[18:21]
	s_waitcnt lgkmcnt(3)
	v_mfma_f32_16x16x32_bf16 v[94:97], v[74:77], v[154:157], v[46:49]
	v_mfma_f32_16x16x32_bf16 v[82:85], v[74:77], v[174:177], v[42:45]
	s_waitcnt lgkmcnt(2)
	v_mfma_f32_16x16x32_bf16 v[98:101], v[66:69], v[154:157], v[38:41]
	v_mfma_f32_16x16x32_bf16 v[90:93], v[66:69], v[174:177], v[34:37]
	s_waitcnt lgkmcnt(1)
	v_mfma_f32_16x16x32_bf16 v[102:105], v[58:61], v[154:157], v[30:33]
	v_mfma_f32_16x16x32_bf16 v[86:89], v[58:61], v[174:177], v[26:29]
	s_waitcnt lgkmcnt(0)
	v_mfma_f32_16x16x32_bf16 v[110:113], v[54:57], v[154:157], v[22:25]
	v_mfma_f32_16x16x32_bf16 v[106:109], v[54:57], v[174:177], v[18:21]
	s_branch .LBB0_2218

; template <bool SEL> ...
;     ...
;         for (int it = it0; it < it0 + 2 && it < n; ++it) {
;             const int j = jhi - it, slot = it & 3;
;             bool selq[2] = {true, true}; bool any[2] = {true, true};
;             if (SEL) {
; #pragma unroll
;                 for (int cg_ = 0; cg_ < 2; ++cg_) {
;                     const unsigned long long wsel = j < 64 ? sw[cg_][0] : sw[cg_][1];
;                     selq[cg_] = ((wsel >> (j & 63)) & 1ull) != 0ull; any[cg_] = __any(selq[cg_]) != 0;
;                 }
;             }
;             if (any[0] || any[1]) {
;                 const unsigned char* Ks = lds + OFF_RING + slot * SLOTB; const unsigned char* Vs = Ks + 8192;
;                 bf16x8 kf[4][2]; load_kfrags(kf, Ks, r, fq);
;                 const bool edge = (j >= T - 2) || (wl == 512 && j == T - 8);
;                 if (edge) {
;                     if (any[0] && any[1]) step_edge<3>(kf, q, tq, j * 64, fq, H, btab, wl, selq, m, l, o, Vs, r);
;                     else if (any[0]) step_edge<1>(kf, q, tq, j * 64, fq, H, btab, wl, selq, m, l, o, Vs, r);
;                     else step_edge<2>(kf, q, tq, j * 64, fq, H, btab, wl, selq, m, l, o, Vs, r);
;                 } else {
;                     if (any[0] && any[1]) step_int<3>(kf, q, farb, selq, m, l, o, Vs, r, fq);
;                     else if (any[0]) step_int<1>(kf, q, farb, selq, m, l, o, Vs, r, fq);
;                     else step_int<2>(kf, q, farb, selq, m, l, o, Vs, r, fq);
;                 }
.LBB0_2482:
	s_cmp_lt_i32 s48, 64
	s_cselect_b64 vcc, -1, 0
	s_waitcnt lgkmcnt(2)
	v_cndmask_b32_e32 v60, v35, v33, vcc
	s_lshl_b64 s[6:7], 1, s48
	v_cndmask_b32_e32 v62, v34, v32, vcc
	v_and_b32_e32 v61, s7, v60
	v_and_b32_e32 v60, s6, v62
	v_cmp_ne_u64_e64 s[10:11], 0, v[60:61]
	v_cndmask_b32_e32 v60, v39, v37, vcc
	v_cndmask_b32_e32 v62, v38, v36, vcc
	v_and_b32_e32 v61, s7, v60
	v_and_b32_e32 v60, s6, v62
	v_cmp_ne_u64_e64 s[8:9], 0, v[60:61]
	s_or_b64 s[6:7], s[10:11], s[8:9]
	s_cmp_lg_u64 s[10:11], 0
	s_cselect_b64 s[12:13], -1, 0
	s_cmp_eq_u64 s[10:11], 0
	s_cselect_b64 s[36:37], -1, 0
	s_cmp_lg_u64 s[8:9], 0
	s_cselect_b64 s[14:15], -1, 0
	s_cmp_lg_u64 s[6:7], 0
	s_cselect_b64 s[6:7], -1, 0
	s_andn2_b64 vcc, exec, s[6:7]
	s_cbranch_vccnz .LBB0_2481
	s_and_b32 s6, s49, 0xc000
	v_add_u32_e32 v60, s6, v140
	v_add_u32_e32 v143, v60, v136
	v_add_u32_e32 v142, v60, v137
	ds_read_b128 v[88:91], v143
	ds_read_b128 v[80:83], v143 offset:512
	ds_read_b128 v[84:87], v142
	ds_read_b128 v[76:79], v142 offset:512
	ds_read_b128 v[72:75], v143 offset:4096
	ds_read_b128 v[60:63], v143 offset:4608
	s_waitcnt lgkmcnt(7)
	ds_read_b128 v[68:71], v142 offset:4096
	s_waitcnt lgkmcnt(7)
	ds_read_b128 v[64:67], v142 offset:4608
	s_and_b64 s[6:7], s[12:13], s[14:15]
	s_xor_b64 s[38:39], s[6:7], -1
	s_cmp_lt_i32 s48, s93
	s_mov_b64 s[12:13], -1
	s_cbranch_scc1 .Lsel_int
	s_branch .Lsel_edge
	s_and_b64 vcc, exec, s[38:39]
	s_cbranch_vccz .LBB0_2557
	s_and_b64 vcc, exec, s[36:37]
	s_cbranch_vccz .LBB0_2521
	s_waitcnt lgkmcnt(7)
	v_mfma_f32_16x16x32_bf16 v[92:95], v[88:91], v[10:13], 0
	v_add_u32_e32 v119, s4, v141
	v_add_u32_e32 v110, 4, v119
	v_cmp_gt_u32_e32 vcc, 2.0, v110
	s_waitcnt lgkmcnt(5)
	v_mfma_f32_16x16x32_bf16 v[104:107], v[84:87], v[14:17], v[92:95]
	v_mov_b32_e32 v108, 0xf149f2ca
	v_mov_b32_e32 v109, 0xf149f2ca
	v_mfma_f32_16x16x32_bf16 v[92:95], v[80:83], v[10:13], 0
	s_waitcnt lgkmcnt(4)
	v_mfma_f32_16x16x32_bf16 v[100:103], v[76:79], v[14:17], v[92:95]
	s_waitcnt lgkmcnt(3)
	v_mfma_f32_16x16x32_bf16 v[92:95], v[72:75], v[10:13], 0
	s_waitcnt lgkmcnt(1)
	v_mfma_f32_16x16x32_bf16 v[96:99], v[68:71], v[14:17], v[92:95]
	v_mfma_f32_16x16x32_bf16 v[92:95], v[60:63], v[10:13], 0
	s_waitcnt lgkmcnt(0)
	v_mfma_f32_16x16x32_bf16 v[92:95], v[64:67], v[14:17], v[92:95]
	s_and_saveexec_b64 s[12:13], vcc
	s_cbranch_execz .LBB0_2488
	v_min_u32_e32 v109, 0x80, v110
	v_lshl_add_u32 v109, v109, 6, v177
	ds_read_b32 v109, v109
	s_waitcnt lgkmcnt(0)
	v_add_f32_e32 v109, v104, v109

; __device__ __forceinline__ void logits(float (&v)[4][4], const f32x4 (&s)[4], int tq, int kpos0, int kstride, int fq, int H, const float* btab, float farb, bool use_tab, int wl) {
; #pragma unroll
;     for (int f = 0; f < 4; ++f)
; #pragma unroll
;         for (int i = 0; i < 4; ++i) {
;             const int kk = 32 * (f >> 1) + 8 * fq + 4 * (f & 1) + i;
;             const int dist = tq - (kpos0 + kstride * kk);
;             const bool ok = dist >= 0 && dist < wl;
;             const int di = dist < 0 ? 0 : (dist > 128 ? 128 : dist);
;             v[f][i] = ok ? s[f][i] + btab[di * 16 + H] : -1e30f;
;         }
; }
; template <int CGM> ...
;     float v[2][4][4]; float mnew[2] = {m[0], m[1]};
; #pragma unroll
;     for (int cg_ = 0; cg_ < 2; ++cg_) if ((CGM >> cg_) & 1) {
;         f32x4 s[4]; qk(s, kf, q[cg_], 0.f); logits(v[cg_], s, tq[cg_], key0, 1, fq, H, btab, 0.f, true, wl);
;         float mx = red_max4(max16(v[cg_])); if (!selq[cg_]) mx = -1e30f; mnew[cg_] = fmaxf(m[cg_], mx);
.Lsel_edge:
	s_mov_b32 s98, 0x40000000
	v_add_u32_e32 v251, s4, v141
	s_waitcnt lgkmcnt(7)
	v_mfma_f32_16x16x32_bf16 v[92:95], v[88:91], v[2:5], 0
	v_mfma_f32_16x16x32_bf16 v[108:111], v[88:91], v[10:13], 0
	s_waitcnt lgkmcnt(6)
	v_mfma_f32_16x16x32_bf16 v[96:99], v[80:83], v[2:5], 0
	v_mfma_f32_16x16x32_bf16 v[112:115], v[80:83], v[10:13], 0
	s_waitcnt lgkmcnt(5)
	v_mfma_f32_16x16x32_bf16 v[92:95], v[84:87], v[6:9], v[92:95]
	v_mfma_f32_16x16x32_bf16 v[108:111], v[84:87], v[14:17], v[108:111]
	s_waitcnt lgkmcnt(4)
	v_mfma_f32_16x16x32_bf16 v[96:99], v[76:79], v[6:9], v[96:99]
	v_mfma_f32_16x16x32_bf16 v[112:115], v[76:79], v[14:17], v[112:115]
	s_waitcnt lgkmcnt(3)
	v_mfma_f32_16x16x32_bf16 v[100:103], v[72:75], v[2:5], 0
	v_mfma_f32_16x16x32_bf16 v[116:119], v[72:75], v[10:13], 0
	s_waitcnt lgkmcnt(2)
	v_mfma_f32_16x16x32_bf16 v[104:107], v[60:63], v[2:5], 0
	v_mfma_f32_16x16x32_bf16 v[120:123], v[60:63], v[10:13], 0
	s_waitcnt lgkmcnt(1)
	v_mfma_f32_16x16x32_bf16 v[100:103], v[68:71], v[6:9], v[100:103]
	v_mfma_f32_16x16x32_bf16 v[116:119], v[68:71], v[14:17], v[116:119]
	s_waitcnt lgkmcnt(0)
	v_mfma_f32_16x16x32_bf16 v[104:107], v[64:67], v[6:9], v[104:107]
	v_mfma_f32_16x16x32_bf16 v[120:123], v[64:67], v[14:17], v[120:123]
	v_add_u32_e32 v255, 0, v251
	v_min_u32_e32 v255, 0x80, v255
	v_lshl_add_u32 v232, v255, 6, v177
	ds_read_b32 v232, v232
	v_add_u32_e32 v255, -1, v251
	v_min_u32_e32 v255, 0x80, v255
	v_lshl_add_u32 v233, v255, 6, v177
	ds_read_b32 v233, v233
	v_add_u32_e32 v255, -2, v251
	v_min_u32_e32 v255, 0x80, v255
	v_lshl_add_u32 v234, v255, 6, v177
	ds_read_b32 v234, v234
	v_add_u32_e32 v255, -3, v251
	v_min_u32_e32 v255, 0x80, v255
	v_lshl_add_u32 v235, v255, 6, v177
	ds_read_b32 v235, v235
	v_add_u32_e32 v255, -4, v251
	v_min_u32_e32 v255, 0x80, v255
	v_lshl_add_u32 v236, v255, 6, v177
	ds_read_b32 v236, v236
	v_add_u32_e32 v255, -5, v251
	v_min_u32_e32 v255, 0x80, v255
	v_lshl_add_u32 v237, v255, 6, v177
	ds_read_b32 v237, v237
	v_add_u32_e32 v255, -6, v251
	v_min_u32_e32 v255, 0x80, v255
	v_lshl_add_u32 v238, v255, 6, v177
	ds_read_b32 v238, v238
	v_add_u32_e32 v255, -7, v251
	v_min_u32_e32 v255, 0x80, v255
	v_lshl_add_u32 v239, v255, 6, v177
	ds_read_b32 v239, v239
	v_add_u32_e32 v255, 0xffffffe0, v251
	v_min_u32_e32 v255, 0x80, v255
	v_lshl_add_u32 v240, v255, 6, v177
	ds_read_b32 v240, v240
	v_add_u32_e32 v255, 0xffffffdf, v251
	v_min_u32_e32 v255, 0x80, v255
	v_lshl_add_u32 v241, v255, 6, v177
	ds_read_b32 v241, v241
	v_add_u32_e32 v255, 0xffffffde, v251
	v_min_u32_e32 v255, 0x80, v255
	v_lshl_add_u32 v242, v255, 6, v177
	ds_read_b32 v242, v242
	v_add_u32_e32 v255, 0xffffffdd, v251
	v_min_u32_e32 v255, 0x80, v255
	v_lshl_add_u32 v243, v255, 6, v177
	ds_read_b32 v243, v243
	v_add_u32_e32 v255, 0xffffffdc, v251
	v_min_u32_e32 v255, 0x80, v255
	v_lshl_add_u32 v244, v255, 6, v177
	ds_read_b32 v244, v244
	v_add_u32_e32 v255, 0xffffffdb, v251
	v_min_u32_e32 v255, 0x80, v255
	v_lshl_add_u32 v245, v255, 6, v177
	ds_read_b32 v245, v245
	v_add_u32_e32 v255, 0xffffffda, v251
	v_min_u32_e32 v255, 0x80, v255
	v_lshl_add_u32 v246, v255, 6, v177
	ds_read_b32 v246, v246
	v_add_u32_e32 v255, 0xffffffd9, v251
	v_min_u32_e32 v255, 0x80, v255
	v_lshl_add_u32 v247, v255, 6, v177
	ds_read_b32 v247, v247
	v_add_u32_e32 v248, 0, v251
	v_cmp_gt_u32_e64 s[6:7], s98, v248
	v_add_u32_e32 v249, -1, v251
	v_cmp_gt_u32_e64 s[12:13], s98, v249
	v_add_u32_e32 v250, -2, v251
	v_cmp_gt_u32_e64 s[14:15], s98, v250
	s_waitcnt lgkmcnt(15)
	v_add_f32_e32 v92, v92, v232
	v_cndmask_b32_e64 v92, v148, v92, s[6:7]
	v_add_u32_e32 v248, -3, v251
	v_cmp_gt_u32_e64 s[6:7], s98, v248
	s_waitcnt lgkmcnt(14)
	v_add_f32_e32 v93, v93, v233
	v_cndmask_b32_e64 v93, v148, v93, s[12:13]
	v_add_u32_e32 v249, -4, v251
	v_cmp_gt_u32_e64 s[12:13], s98, v249
	s_waitcnt lgkmcnt(13)
	v_add_f32_e32 v94, v94, v234
	v_cndmask_b32_e64 v94, v148, v94, s[14:15]
	v_add_u32_e32 v250, -5, v251
	v_cmp_gt_u32_e64 s[14:15], s98, v250
	s_waitcnt lgkmcnt(12)
	v_add_f32_e32 v95, v95, v235
	v_cndmask_b32_e64 v95, v148, v95, s[6:7]
	v_add_u32_e32 v248, -6, v251
	v_cmp_gt_u32_e64 s[6:7], s98, v248
	s_waitcnt lgkmcnt(11)
	v_add_f32_e32 v96, v96, v236
	v_cndmask_b32_e64 v96, v148, v96, s[12:13]
	v_add_u32_e32 v249, -7, v251
	v_cmp_gt_u32_e64 s[12:13], s98, v249
	s_waitcnt lgkmcnt(10)
	v_add_f32_e32 v97, v97, v237
	v_cndmask_b32_e64 v97, v148, v97, s[14:15]
	v_add_u32_e32 v250, 0xffffffe0, v251
	v_cmp_gt_u32_e64 s[14:15], s98, v250
	s_waitcnt lgkmcnt(9)
	v_add_f32_e32 v98, v98, v238
	v_cndmask_b32_e64 v98, v148, v98, s[6:7]
	v_add_u32_e32 v248, 0xffffffdf, v251
	v_cmp_gt_u32_e64 s[6:7], s98, v248
	s_waitcnt lgkmcnt(8)
	v_add_f32_e32 v99, v99, v239
	v_cndmask_b32_e64 v99, v148, v99, s[12:13]
	v_add_u32_e32 v249, 0xffffffde, v251
	v_cmp_gt_u32_e64 s[12:13], s98, v249
	s_waitcnt lgkmcnt(7)
	v_add_f32_e32 v100, v100, v240
	v_cndmask_b32_e64 v100, v148, v100, s[14:15]
	v_add_u32_e32 v250, 0xffffffdd, v251
	v_cmp_gt_u32_e64 s[14:15], s98, v250
	s_waitcnt lgkmcnt(6)
	v_add_f32_e32 v101, v101, v241
	v_cndmask_b32_e64 v101, v148, v101, s[6:7]
	v_add_u32_e32 v248, 0xffffffdc, v251
	v_cmp_gt_u32_e64 s[6:7], s98, v248
	s_waitcnt lgkmcnt(5)
	v_add_f32_e32 v102, v102, v242
	v_cndmask_b32_e64 v102, v148, v102, s[12:13]
	v_add_u32_e32 v249, 0xffffffdb, v251
	v_cmp_gt_u32_e64 s[12:13], s98, v249
	s_waitcnt lgkmcnt(4)
	v_add_f32_e32 v103, v103, v243
	v_cndmask_b32_e64 v103, v148, v103, s[14:15]
	v_add_u32_e32 v250, 0xffffffda, v251
	v_cmp_gt_u32_e64 s[14:15], s98, v250
	s_waitcnt lgkmcnt(3)
	v_add_f32_e32 v104, v104, v244
	v_cndmask_b32_e64 v104, v148, v104, s[6:7]
	v_add_u32_e32 v248, 0xffffffd9, v251
	v_cmp_gt_u32_e64 s[6:7], s98, v248
	s_waitcnt lgkmcnt(2)
; __device__ __forceinline__ void logits(float (&v)[4][4], const f32x4 (&s)[4], int tq, int kpos0, int kstride, int fq, int H, const float* btab, float farb, bool use_tab, int wl) {
; #pragma unroll
;     for (int f = 0; f < 4; ++f)
; #pragma unroll
;         for (int i = 0; i < 4; ++i) {
;             const int kk = 32 * (f >> 1) + 8 * fq + 4 * (f & 1) + i;
;             const int dist = tq - (kpos0 + kstride * kk);
;             const bool ok = dist >= 0 && dist < wl;
;             const int di = dist < 0 ? 0 : (dist > 128 ? 128 : dist);
;             v[f][i] = ok ? s[f][i] + btab[di * 16 + H] : -1e30f;
;         }
; }
; __device__ __forceinline__ float red_max4(float x) {
;     auto a = __builtin_amdgcn_permlane16_swap(__float_as_uint(x), __float_as_uint(x), false, false); x = fmaxf(__uint_as_float(a[0]), __uint_as_float(a[1]));
;     auto b = __builtin_amdgcn_permlane32_swap(__float_as_uint(x), __float_as_uint(x), false, false); return fmaxf(__uint_as_float(b[0]), __uint_as_float(b[1]));
; }
; __device__ __forceinline__ float quad_sum(float x) {
;     auto a = __builtin_amdgcn_permlane16_swap(__float_as_uint(x), __float_as_uint(x), false, false); x = __uint_as_float(a[0]) + __uint_as_float(a[1]);
;     auto b = __builtin_amdgcn_permlane32_swap(__float_as_uint(x), __float_as_uint(x), false, false); return __uint_as_float(b[0]) + __uint_as_float(b[1]);
; }
; __device__ __forceinline__ float dpp_xor1(float x) { return __builtin_bit_cast(float, __builtin_amdgcn_update_dpp(0, __builtin_bit_cast(int, x), 0xB1, 0xF, 0xF, true)); }
; __device__ __forceinline__ float dpp_xor2(float x) { return __builtin_bit_cast(float, __builtin_amdgcn_update_dpp(0, __builtin_bit_cast(int, x), 0x4E, 0xF, 0xF, true)); }
; __device__ __forceinline__ float max16(const float (&v)[4][4]) {
;     float a = fmaxf(fmaxf(v[0][0], v[0][1]), fmaxf(v[0][2], v[0][3])), b = fmaxf(fmaxf(v[1][0], v[1][1]), fmaxf(v[1][2], v[1][3]));
;     float c = fmaxf(fmaxf(v[2][0], v[2][1]), fmaxf(v[2][2], v[2][3])), d = fmaxf(fmaxf(v[3][0], v[3][1]), fmaxf(v[3][2], v[3][3]));
;     return fmaxf(fmaxf(a, b), fmaxf(c, d));
; }
; __device__ __forceinline__ float max3f(float a, float b, float c) { float r; asm("v_max3_f32 %0, %1, %2, %3" : "=v"(r) : "v"(a), "v"(b), "v"(c)); return r; }
; __device__ __forceinline__ float max16v(const f32x4 (&s)[4]) {
	v_add_f32_e32 v105, v105, v245
	v_cndmask_b32_e64 v105, v148, v105, s[12:13]
	s_waitcnt lgkmcnt(1)
	v_add_f32_e32 v106, v106, v246
	v_cndmask_b32_e64 v106, v148, v106, s[14:15]
	s_waitcnt lgkmcnt(0)
	v_add_f32_e32 v107, v107, v247
	v_cndmask_b32_e64 v107, v148, v107, s[6:7]
	v_add_u32_e32 v255, 4, v251
	v_min_u32_e32 v255, 0x80, v255
	v_lshl_add_u32 v232, v255, 6, v177
	ds_read_b32 v232, v232
	v_add_u32_e32 v255, 3, v251
	v_min_u32_e32 v255, 0x80, v255
	v_lshl_add_u32 v233, v255, 6, v177
	ds_read_b32 v233, v233
	v_add_u32_e32 v255, 2, v251
	v_min_u32_e32 v255, 0x80, v255
	v_lshl_add_u32 v234, v255, 6, v177
	ds_read_b32 v234, v234
	v_add_u32_e32 v255, 1, v251
	v_min_u32_e32 v255, 0x80, v255
	v_lshl_add_u32 v235, v255, 6, v177
	ds_read_b32 v235, v235
	v_add_u32_e32 v255, 0, v251
	v_min_u32_e32 v255, 0x80, v255
	v_lshl_add_u32 v236, v255, 6, v177
	ds_read_b32 v236, v236
	v_add_u32_e32 v255, -1, v251
	v_min_u32_e32 v255, 0x80, v255
	v_lshl_add_u32 v237, v255, 6, v177
	ds_read_b32 v237, v237
	v_add_u32_e32 v255, -2, v251
	v_min_u32_e32 v255, 0x80, v255
	v_lshl_add_u32 v238, v255, 6, v177
	ds_read_b32 v238, v238
	v_add_u32_e32 v255, -3, v251
	v_min_u32_e32 v255, 0x80, v255
	v_lshl_add_u32 v239, v255, 6, v177
	ds_read_b32 v239, v239
	v_add_u32_e32 v255, 0xffffffe4, v251
	v_min_u32_e32 v255, 0x80, v255
	v_lshl_add_u32 v240, v255, 6, v177
	ds_read_b32 v240, v240
	v_add_u32_e32 v255, 0xffffffe3, v251
	v_min_u32_e32 v255, 0x80, v255
	v_lshl_add_u32 v241, v255, 6, v177
	ds_read_b32 v241, v241
	v_add_u32_e32 v255, 0xffffffe2, v251
	v_min_u32_e32 v255, 0x80, v255
	v_lshl_add_u32 v242, v255, 6, v177
	ds_read_b32 v242, v242
	v_add_u32_e32 v255, 0xffffffe1, v251
	v_min_u32_e32 v255, 0x80, v255
	v_lshl_add_u32 v243, v255, 6, v177
	ds_read_b32 v243, v243
	v_add_u32_e32 v255, 0xffffffe0, v251
	v_min_u32_e32 v255, 0x80, v255
	v_lshl_add_u32 v244, v255, 6, v177
	ds_read_b32 v244, v244
	v_add_u32_e32 v255, 0xffffffdf, v251
	v_min_u32_e32 v255, 0x80, v255
	v_lshl_add_u32 v245, v255, 6, v177
	ds_read_b32 v245, v245
	v_add_u32_e32 v255, 0xffffffde, v251
	v_min_u32_e32 v255, 0x80, v255
	v_lshl_add_u32 v246, v255, 6, v177
	ds_read_b32 v246, v246
	v_add_u32_e32 v255, 0xffffffdd, v251
	v_min_u32_e32 v255, 0x80, v255
	v_lshl_add_u32 v247, v255, 6, v177
	ds_read_b32 v247, v247
	v_add_u32_e32 v248, 4, v251
	v_cmp_gt_u32_e64 s[6:7], s98, v248
	v_add_u32_e32 v249, 3, v251
	v_cmp_gt_u32_e64 s[12:13], s98, v249
	v_add_u32_e32 v250, 2, v251
	v_cmp_gt_u32_e64 s[14:15], s98, v250
	s_waitcnt lgkmcnt(15)
	v_add_f32_e32 v108, v108, v232
	v_cndmask_b32_e64 v108, v148, v108, s[6:7]
	v_add_u32_e32 v248, 1, v251
	v_cmp_gt_u32_e64 s[6:7], s98, v248
	s_waitcnt lgkmcnt(14)
	v_add_f32_e32 v109, v109, v233
	v_cndmask_b32_e64 v109, v148, v109, s[12:13]
	v_add_u32_e32 v249, 0, v251
	v_cmp_gt_u32_e64 s[12:13], s98, v249
	s_waitcnt lgkmcnt(13)
	v_add_f32_e32 v110, v110, v234
	v_cndmask_b32_e64 v110, v148, v110, s[14:15]
	v_add_u32_e32 v250, -1, v251
	v_cmp_gt_u32_e64 s[14:15], s98, v250
	s_waitcnt lgkmcnt(12)
	v_add_f32_e32 v111, v111, v235
	v_cndmask_b32_e64 v111, v148, v111, s[6:7]
	v_add_u32_e32 v248, -2, v251
	v_cmp_gt_u32_e64 s[6:7], s98, v248
	s_waitcnt lgkmcnt(11)
	v_add_f32_e32 v112, v112, v236
	v_cndmask_b32_e64 v112, v148, v112, s[12:13]
	v_add_u32_e32 v249, -3, v251
	v_cmp_gt_u32_e64 s[12:13], s98, v249
	s_waitcnt lgkmcnt(10)
	v_add_f32_e32 v113, v113, v237
	v_cndmask_b32_e64 v113, v148, v113, s[14:15]
	v_add_u32_e32 v250, 0xffffffe4, v251
	v_cmp_gt_u32_e64 s[14:15], s98, v250
	s_waitcnt lgkmcnt(9)
	v_add_f32_e32 v114, v114, v238
	v_cndmask_b32_e64 v114, v148, v114, s[6:7]
	v_add_u32_e32 v248, 0xffffffe3, v251
	v_cmp_gt_u32_e64 s[6:7], s98, v248
	s_waitcnt lgkmcnt(8)
	v_add_f32_e32 v115, v115, v239
	v_cndmask_b32_e64 v115, v148, v115, s[12:13]
	v_add_u32_e32 v249, 0xffffffe2, v251
	v_cmp_gt_u32_e64 s[12:13], s98, v249
	s_waitcnt lgkmcnt(7)
	v_add_f32_e32 v116, v116, v240
	v_cndmask_b32_e64 v116, v148, v116, s[14:15]
	v_add_u32_e32 v250, 0xffffffe1, v251
	v_cmp_gt_u32_e64 s[14:15], s98, v250
	s_waitcnt lgkmcnt(6)
	v_add_f32_e32 v117, v117, v241
	v_cndmask_b32_e64 v117, v148, v117, s[6:7]
	v_add_u32_e32 v248, 0xffffffe0, v251
	v_cmp_gt_u32_e64 s[6:7], s98, v248
	s_waitcnt lgkmcnt(5)
	v_add_f32_e32 v118, v118, v242
	v_cndmask_b32_e64 v118, v148, v118, s[12:13]
	v_add_u32_e32 v249, 0xffffffdf, v251
	v_cmp_gt_u32_e64 s[12:13], s98, v249
	s_waitcnt lgkmcnt(4)
	v_add_f32_e32 v119, v119, v243
	v_cndmask_b32_e64 v119, v148, v119, s[14:15]
	v_add_u32_e32 v250, 0xffffffde, v251
	v_cmp_gt_u32_e64 s[14:15], s98, v250
	s_waitcnt lgkmcnt(3)
	v_add_f32_e32 v120, v120, v244
	v_cndmask_b32_e64 v120, v148, v120, s[6:7]
	v_add_u32_e32 v248, 0xffffffdd, v251
	v_cmp_gt_u32_e64 s[6:7], s98, v248
	s_waitcnt lgkmcnt(2)
	v_add_f32_e32 v121, v121, v245
	v_cndmask_b32_e64 v121, v148, v121, s[12:13]
	s_waitcnt lgkmcnt(1)
	v_add_f32_e32 v122, v122, v246
	v_cndmask_b32_e64 v122, v148, v122, s[14:15]
	s_waitcnt lgkmcnt(0)
	v_add_f32_e32 v123, v123, v247
	v_cndmask_b32_e64 v123, v148, v123, s[6:7]
	ds_read_b128 v[88:91], v143 offset:8192
	ds_read_b128 v[80:83], v143 offset:8704
	ds_read_b128 v[72:75], v143 offset:12288
	ds_read_b128 v[60:63], v143 offset:12800
	ds_read_b128 v[84:87], v142 offset:8192
	ds_read_b128 v[76:79], v142 offset:8704
	ds_read_b128 v[68:71], v142 offset:12288
	ds_read_b128 v[64:67], v142 offset:12800
	v_max3_f32 v128, v92, v93, v94
	v_max3_f32 v129, v95, v96, v97
	v_max3_f32 v130, v98, v99, v100
	v_max3_f32 v131, v101, v102, v103
	v_max3_f32 v144, v108, v109, v110
	v_max3_f32 v145, v111, v112, v113
	v_max3_f32 v146, v114, v115, v116
	v_max3_f32 v147, v117, v118, v119
	v_max3_f32 v128, v128, v104, v105
	v_max3_f32 v129, v129, v106, v107
	v_max3_f32 v144, v144, v120, v121
	v_max3_f32 v145, v145, v122, v123
	v_max3_f32 v128, v128, v129, v130
	v_max3_f32 v144, v144, v145, v146
	v_max_f32_e32 v128, v128, v131
	v_max_f32_e32 v144, v144, v147
	v_mov_b32_e32 v129, v128
	v_mov_b32_e32 v145, v144
	s_nop 1
	v_permlane16_swap_b32_e32 v128, v129
	v_permlane16_swap_b32_e32 v144, v145
	v_max_f32_e32 v128, v128, v129
	v_max_f32_e32 v144, v144, v145
	v_mov_b32_e32 v129, v128
	v_mov_b32_e32 v145, v144
	s_nop 1
	v_permlane32_swap_b32_e32 v128, v129
	v_permlane32_swap_b32_e32 v144, v145
	v_max_f32_e32 v128, v128, v129
	v_max_f32_e32 v144, v144, v145
	v_cndmask_b32_e64 v128, v148, v128, s[10:11]
	v_cndmask_b32_e64 v144, v148, v144, s[8:9]
	v_max_f32_e32 v129, v124, v128
	v_max_f32_e32 v145, v125, v144
	v_cmp_gt_f32_e32 vcc, v129, v124
	v_cmp_gt_f32_e64 s[6:7], v145, v125
	s_or_b64 vcc, vcc, s[6:7]
	s_cbranch_vccz .Lsel_edge_nors
; __device__ __forceinline__ unsigned cvt_pk_bf16(float lo, float hi) { unsigned r; asm volatile("v_cvt_pk_bf16_f32 %0, %1, %2" : "=v"(r) : "v"(lo), "v"(hi)); return r; }
; __device__ __forceinline__ int swz(int R) { return (R & 2) | ((R & 8) >> 1); }
; template <int CGM>
; __device__ __forceinline__ void pv2(f32x4 (&o)[2][4], const float (&p)[2][4][4], const unsigned char* Vs, int r, int fq) {
;     bf16x8 pb[2][2];
; #pragma unroll
;     for (int cg_ = 0; cg_ < 2; ++cg_) if ((CGM >> cg_) & 1)
; #pragma unroll
;         for (int kc = 0; kc < 2; ++kc) {
;             u32x4 w; w.x = cvt_pk_bf16(p[cg_][2 * kc][0], p[cg_][2 * kc][1]); w.y = cvt_pk_bf16(p[cg_][2 * kc][2], p[cg_][2 * kc][3]);
;             w.z = cvt_pk_bf16(p[cg_][2 * kc + 1][0], p[cg_][2 * kc + 1][1]); w.w = cvt_pk_bf16(p[cg_][2 * kc + 1][2], p[cg_][2 * kc + 1][3]);
;             pb[cg_][kc] = __builtin_bit_cast(bf16x8, w);
;         }
; #pragma unroll
;     for (int df = 0; df < 4; ++df)
; #pragma unroll
;         for (int kc = 0; kc < 2; ++kc) {
;             const int R = prow(df, r);
;             const bf16x8 vf = *(const bf16x8*)(Vs + R * 128 + (((4 * kc + fq) ^ swz(R)) << 4));
;             if (CGM & 1) o[0][df] = __builtin_amdgcn_mfma_f32_16x16x32_bf16(vf, pb[0][kc], o[0][df], 0, 0, 0);
;             if (CGM & 2) o[1][df] = __builtin_amdgcn_mfma_f32_16x16x32_bf16(vf, pb[1][kc], o[1][df], 0, 0, 0);
;         }
; }
; template <int CGM> ...
;     ...
;     if (__any(mnew[0] > m[0] || mnew[1] > m[1])) {
; #pragma unroll
;         for (int cg_ = 0; cg_ < 2; ++cg_) if ((CGM >> cg_) & 1) {
;             const float sc = __builtin_amdgcn_exp2f(m[cg_] - mnew[cg_]); l[cg_] *= sc; m[cg_] = mnew[cg_];
; #pragma unroll
;             for (int df = 0; df < 4; ++df) o[cg_][df] *= sc;
;         }
;     }
; #pragma unroll
;     for (int cg_ = 0; cg_ < 2; ++cg_) if ((CGM >> cg_) & 1) {
;         const float moff = selq[cg_] ? m[cg_] : 1e30f; float rs = 0.f;
; #pragma unroll
;         for (int f = 0; f < 4; ++f)
; #pragma unroll
;             for (int i = 0; i < 4; ++i) { const float pe = __builtin_amdgcn_exp2f(v[cg_][f][i] - moff); v[cg_][f][i] = pe; rs += pe; }
;         l[cg_] += rs;
;     }
;     pv2<CGM>(o, v, Vs, r, fq);
; }
	v_sub_f32_e32 v128, v124, v129
	v_sub_f32_e32 v146, v125, v145
	v_exp_f32_e32 v128, v128
	v_exp_f32_e32 v146, v146
	v_mov_b32_e32 v124, v129
	v_mov_b32_e32 v125, v145
	v_mul_f32_e32 v127, v127, v128
	v_pk_mul_f32 v[56:57], v[56:57], v[128:129] op_sel_hi:[1,0]
	v_pk_mul_f32 v[58:59], v[58:59], v[128:129] op_sel_hi:[1,0]
	v_pk_mul_f32 v[52:53], v[52:53], v[128:129] op_sel_hi:[1,0]
	v_pk_mul_f32 v[54:55], v[54:55], v[128:129] op_sel_hi:[1,0]
	v_pk_mul_f32 v[48:49], v[48:49], v[128:129] op_sel_hi:[1,0]
	v_pk_mul_f32 v[50:51], v[50:51], v[128:129] op_sel_hi:[1,0]
	v_pk_mul_f32 v[44:45], v[44:45], v[128:129] op_sel_hi:[1,0]
	v_pk_mul_f32 v[46:47], v[46:47], v[128:129] op_sel_hi:[1,0]
	v_mul_f32_e32 v126, v126, v146
	v_pk_mul_f32 v[40:41], v[40:41], v[146:147] op_sel_hi:[1,0]
	v_pk_mul_f32 v[42:43], v[42:43], v[146:147] op_sel_hi:[1,0]
	v_pk_mul_f32 v[28:29], v[28:29], v[146:147] op_sel_hi:[1,0]
	v_pk_mul_f32 v[30:31], v[30:31], v[146:147] op_sel_hi:[1,0]
	v_pk_mul_f32 v[24:25], v[24:25], v[146:147] op_sel_hi:[1,0]
	v_pk_mul_f32 v[26:27], v[26:27], v[146:147] op_sel_hi:[1,0]
	v_pk_mul_f32 v[20:21], v[20:21], v[146:147] op_sel_hi:[1,0]
	v_pk_mul_f32 v[22:23], v[22:23], v[146:147] op_sel_hi:[1,0]
.Lsel_edge_nors:
	v_mov_b32_e32 v130, 0x7149f2ca
	v_cndmask_b32_e64 v130, v130, v124, s[10:11]
	v_mov_b32_e32 v147, 0x7149f2ca
	v_cndmask_b32_e64 v147, v147, v125, s[8:9]
	v_sub_f32_e32 v92, v92, v130
	v_sub_f32_e32 v93, v93, v130
	v_sub_f32_e32 v94, v94, v130
	v_sub_f32_e32 v95, v95, v130
	v_sub_f32_e32 v96, v96, v130
	v_sub_f32_e32 v97, v97, v130
	v_sub_f32_e32 v98, v98, v130
	v_sub_f32_e32 v99, v99, v130
	v_sub_f32_e32 v100, v100, v130
	v_sub_f32_e32 v101, v101, v130
	v_sub_f32_e32 v102, v102, v130
	v_sub_f32_e32 v103, v103, v130
	v_sub_f32_e32 v104, v104, v130
	v_sub_f32_e32 v105, v105, v130
	v_sub_f32_e32 v106, v106, v130
	v_sub_f32_e32 v107, v107, v130
	v_sub_f32_e32 v108, v108, v147
	v_sub_f32_e32 v109, v109, v147
	v_sub_f32_e32 v110, v110, v147
	v_sub_f32_e32 v111, v111, v147
	v_sub_f32_e32 v112, v112, v147
	v_sub_f32_e32 v113, v113, v147
	v_sub_f32_e32 v114, v114, v147
	v_sub_f32_e32 v115, v115, v147
	v_sub_f32_e32 v116, v116, v147
	v_sub_f32_e32 v117, v117, v147
	v_sub_f32_e32 v118, v118, v147
	v_sub_f32_e32 v119, v119, v147
	v_sub_f32_e32 v120, v120, v147
	v_sub_f32_e32 v121, v121, v147
	v_sub_f32_e32 v122, v122, v147
	v_sub_f32_e32 v123, v123, v147
	v_exp_f32_e32 v92, v92
	v_exp_f32_e32 v93, v93
	v_exp_f32_e32 v94, v94
	v_exp_f32_e32 v95, v95
	v_exp_f32_e32 v96, v96
	v_exp_f32_e32 v97, v97
	v_exp_f32_e32 v98, v98
	v_exp_f32_e32 v99, v99
	v_exp_f32_e32 v100, v100
	v_exp_f32_e32 v101, v101
	v_exp_f32_e32 v102, v102
	v_exp_f32_e32 v103, v103
	v_exp_f32_e32 v104, v104
	v_exp_f32_e32 v105, v105
	v_exp_f32_e32 v106, v106
	v_exp_f32_e32 v107, v107
	v_exp_f32_e32 v108, v108
	v_exp_f32_e32 v109, v109
	v_exp_f32_e32 v110, v110
	v_exp_f32_e32 v111, v111
	v_exp_f32_e32 v112, v112
	v_exp_f32_e32 v113, v113
	v_exp_f32_e32 v114, v114
	v_exp_f32_e32 v115, v115
	v_exp_f32_e32 v116, v116
	v_exp_f32_e32 v117, v117
	v_exp_f32_e32 v118, v118
	v_exp_f32_e32 v119, v119
	v_exp_f32_e32 v120, v120
	v_exp_f32_e32 v121, v121
	v_exp_f32_e32 v122, v122
	v_exp_f32_e32 v123, v123
	v_pk_add_f32 v[130:131], v[92:93], v[94:95]
	v_pk_add_f32 v[130:131], v[130:131], v[96:97]
	v_pk_add_f32 v[130:131], v[130:131], v[98:99]
	v_pk_add_f32 v[130:131], v[130:131], v[100:101]
	v_pk_add_f32 v[130:131], v[130:131], v[102:103]
	v_pk_add_f32 v[130:131], v[130:131], v[104:105]
	v_pk_add_f32 v[130:131], v[130:131], v[106:107]
	v_pk_add_f32 v[146:147], v[108:109], v[110:111]
	v_pk_add_f32 v[146:147], v[146:147], v[112:113]
	v_pk_add_f32 v[146:147], v[146:147], v[114:115]
	v_pk_add_f32 v[146:147], v[146:147], v[116:117]
	v_pk_add_f32 v[146:147], v[146:147], v[118:119]
	v_pk_add_f32 v[146:147], v[146:147], v[120:121]
	v_pk_add_f32 v[146:147], v[146:147], v[122:123]
	v_add_f32_e32 v130, v130, v131
	v_add_f32_e32 v146, v146, v147
	v_add_f32_e32 v127, v127, v130
	v_add_f32_e32 v126, v126, v146
	v_cvt_pk_bf16_f32 v92, v92, v93
	v_cvt_pk_bf16_f32 v93, v94, v95
	v_cvt_pk_bf16_f32 v94, v96, v97
	v_cvt_pk_bf16_f32 v95, v98, v99
	v_cvt_pk_bf16_f32 v96, v100, v101
	v_cvt_pk_bf16_f32 v97, v102, v103
	v_cvt_pk_bf16_f32 v98, v104, v105
	v_cvt_pk_bf16_f32 v99, v106, v107
	v_cvt_pk_bf16_f32 v108, v108, v109
	v_cvt_pk_bf16_f32 v109, v110, v111
	v_cvt_pk_bf16_f32 v110, v112, v113
	v_cvt_pk_bf16_f32 v111, v114, v115
	v_cvt_pk_bf16_f32 v112, v116, v117
	v_cvt_pk_bf16_f32 v113, v118, v119
	v_cvt_pk_bf16_f32 v114, v120, v121
	v_cvt_pk_bf16_f32 v115, v122, v123
	s_nop 0
	s_waitcnt lgkmcnt(7)
	v_mfma_f32_16x16x32_bf16 v[56:59], v[88:91], v[92:95], v[56:59]
	v_mfma_f32_16x16x32_bf16 v[40:43], v[88:91], v[108:111], v[40:43]
	s_waitcnt lgkmcnt(6)
	v_mfma_f32_16x16x32_bf16 v[52:55], v[80:83], v[92:95], v[52:55]
	v_mfma_f32_16x16x32_bf16 v[28:31], v[80:83], v[108:111], v[28:31]
	s_waitcnt lgkmcnt(5)
	v_mfma_f32_16x16x32_bf16 v[48:51], v[72:75], v[92:95], v[48:51]
	v_mfma_f32_16x16x32_bf16 v[24:27], v[72:75], v[108:111], v[24:27]
	s_waitcnt lgkmcnt(4)
	v_mfma_f32_16x16x32_bf16 v[44:47], v[60:63], v[92:95], v[44:47]
	v_mfma_f32_16x16x32_bf16 v[20:23], v[60:63], v[108:111], v[20:23]
	s_waitcnt lgkmcnt(3)
	v_mfma_f32_16x16x32_bf16 v[56:59], v[84:87], v[96:99], v[56:59]
	v_mfma_f32_16x16x32_bf16 v[40:43], v[84:87], v[112:115], v[40:43]
	s_waitcnt lgkmcnt(2)
	v_mfma_f32_16x16x32_bf16 v[52:55], v[76:79], v[96:99], v[52:55]
	v_mfma_f32_16x16x32_bf16 v[28:31], v[76:79], v[112:115], v[28:31]
	s_waitcnt lgkmcnt(1)
	v_mfma_f32_16x16x32_bf16 v[48:51], v[68:71], v[96:99], v[48:51]
	v_mfma_f32_16x16x32_bf16 v[24:27], v[68:71], v[112:115], v[24:27]
	s_waitcnt lgkmcnt(0)
	v_mfma_f32_16x16x32_bf16 v[44:47], v[64:67], v[96:99], v[44:47]
	v_mfma_f32_16x16x32_bf16 v[20:23], v[64:67], v[112:115], v[20:23]
	s_branch .LBB0_2481
; template <int CGM>
; __device__ __forceinline__ void step_int(const bf16x8 (&kf)[4][2], const bf16x8 (&q)[2][2], float farb, const bool (&selq)[2],
;                                          float (&m)[2], float (&l)[2], f32x4 (&o)[2][4], const unsigned char* Vs, int r, int fq) {
;     f32x4 s[2][4]; float mx[2] = {-1e30f, -1e30f};
; #pragma unroll
;     for (int cg_ = 0; cg_ < 2; ++cg_) if ((CGM >> cg_) & 1) { qk(s[cg_], kf, q[cg_], selq[cg_] ? farb - m[cg_] : -1e30f); mx[cg_] = red_max4(max16v(s[cg_])); }
;     if (__any(mx[0] > 0.f || mx[1] > 0.f)) {
; #pragma unroll
;         for (int cg_ = 0; cg_ < 2; ++cg_) if ((CGM >> cg_) & 1) {
;             const float d = fmaxf(mx[cg_], 0.f), sc = __builtin_amdgcn_exp2f(-d); m[cg_] += d; l[cg_] *= sc;
; #pragma unroll
;             for (int df = 0; df < 4; ++df) o[cg_][df] *= sc;
; #pragma unroll
;             for (int f = 0; f < 4; ++f) s[cg_][f] -= d;
;         }
;     }
.Lsel_int:
	s_cmp_lg_u64 s[10:11], 0
	s_cbranch_scc0 .Lsel_c2
	s_cmp_lg_u64 s[8:9], 0
	s_cbranch_scc0 .Lsel_c1
.Lsel_c3:
	v_sub_f32_e32 v128, v18, v124
	v_sub_f32_e32 v144, v18, v125
	v_cndmask_b32_e64 v128, v148, v128, s[10:11]
	v_cndmask_b32_e64 v144, v148, v144, s[8:9]
	v_mov_b32_e32 v129, v128
	v_mov_b32_e32 v130, v128
	v_mov_b32_e32 v131, v128
	v_mov_b32_e32 v145, v144
	v_mov_b32_e32 v146, v144
	v_mov_b32_e32 v147, v144
	s_waitcnt lgkmcnt(7)
	v_mfma_f32_16x16x32_bf16 v[92:95], v[88:91], v[2:5], v[128:131]
	v_mfma_f32_16x16x32_bf16 v[108:111], v[88:91], v[10:13], v[144:147]
	s_waitcnt lgkmcnt(6)
	v_mfma_f32_16x16x32_bf16 v[96:99], v[80:83], v[2:5], v[128:131]
	v_mfma_f32_16x16x32_bf16 v[112:115], v[80:83], v[10:13], v[144:147]
	s_waitcnt lgkmcnt(5)
	v_mfma_f32_16x16x32_bf16 v[92:95], v[84:87], v[6:9], v[92:95]
	v_mfma_f32_16x16x32_bf16 v[108:111], v[84:87], v[14:17], v[108:111]
	s_waitcnt lgkmcnt(4)
	v_mfma_f32_16x16x32_bf16 v[96:99], v[76:79], v[6:9], v[96:99]
	v_mfma_f32_16x16x32_bf16 v[112:115], v[76:79], v[14:17], v[112:115]
	s_waitcnt lgkmcnt(3)
	v_mfma_f32_16x16x32_bf16 v[100:103], v[72:75], v[2:5], v[128:131]
	v_mfma_f32_16x16x32_bf16 v[116:119], v[72:75], v[10:13], v[144:147]
	s_waitcnt lgkmcnt(2)
	v_mfma_f32_16x16x32_bf16 v[104:107], v[60:63], v[2:5], v[128:131]
	v_mfma_f32_16x16x32_bf16 v[120:123], v[60:63], v[10:13], v[144:147]
	s_waitcnt lgkmcnt(1)
	v_mfma_f32_16x16x32_bf16 v[100:103], v[68:71], v[6:9], v[100:103]
	v_mfma_f32_16x16x32_bf16 v[116:119], v[68:71], v[14:17], v[116:119]
	s_waitcnt lgkmcnt(0)
	v_mfma_f32_16x16x32_bf16 v[104:107], v[64:67], v[6:9], v[104:107]
	v_mfma_f32_16x16x32_bf16 v[120:123], v[64:67], v[14:17], v[120:123]
	ds_read_b128 v[88:91], v143 offset:8192
	ds_read_b128 v[80:83], v143 offset:8704
	ds_read_b128 v[72:75], v143 offset:12288
	ds_read_b128 v[60:63], v143 offset:12800
	ds_read_b128 v[84:87], v142 offset:8192
	ds_read_b128 v[76:79], v142 offset:8704
	ds_read_b128 v[68:71], v142 offset:12288
	ds_read_b128 v[64:67], v142 offset:12800
	v_max3_f32 v128, v92, v93, v94
	v_max3_f32 v129, v95, v96, v97
	v_max3_f32 v130, v98, v99, v100
	v_max3_f32 v131, v101, v102, v103
	v_max3_f32 v144, v108, v109, v110
	v_max3_f32 v145, v111, v112, v113
	v_max3_f32 v146, v114, v115, v116
	v_max3_f32 v147, v117, v118, v119
	v_max3_f32 v128, v128, v104, v105
	v_max3_f32 v129, v129, v106, v107
	v_max3_f32 v144, v144, v120, v121
	v_max3_f32 v145, v145, v122, v123
	v_max3_f32 v128, v128, v129, v130
	v_max3_f32 v144, v144, v145, v146
	v_max_f32_e32 v128, v128, v131
	v_max_f32_e32 v144, v144, v147
	v_mov_b32_e32 v129, v128
	v_mov_b32_e32 v145, v144
	s_nop 1
	v_permlane16_swap_b32_e32 v128, v129
	v_permlane16_swap_b32_e32 v144, v145
	v_max_f32_e32 v128, v128, v129
	v_max_f32_e32 v144, v144, v145
	v_mov_b32_e32 v129, v128
	v_mov_b32_e32 v145, v144
	s_nop 1
	v_permlane32_swap_b32_e32 v128, v129
	v_permlane32_swap_b32_e32 v144, v145
	v_max_f32_e32 v128, v128, v129
	v_max_f32_e32 v144, v144, v145
	v_max_f32_e32 v129, v128, v144
	v_cmp_lt_f32_e32 vcc, 0, v129
	s_cbranch_vccz .Lsel_c3_exp
	v_max_f32_e32 v130, 0, v128
	v_max_f32_e32 v147, 0, v144
	v_exp_f32_e64 v128, -v130
	v_exp_f32_e64 v146, -v147
	v_add_f32_e32 v124, v124, v130
	v_add_f32_e32 v125, v125, v147
	v_sub_f32_e32 v92, v92, v130
	v_sub_f32_e32 v93, v93, v130
	v_sub_f32_e32 v94, v94, v130
	v_sub_f32_e32 v95, v95, v130
	v_sub_f32_e32 v96, v96, v130
	v_sub_f32_e32 v97, v97, v130
	v_sub_f32_e32 v98, v98, v130
	v_sub_f32_e32 v99, v99, v130
	v_sub_f32_e32 v100, v100, v130
	v_sub_f32_e32 v101, v101, v130
	v_sub_f32_e32 v102, v102, v130
	v_sub_f32_e32 v103, v103, v130
	v_sub_f32_e32 v104, v104, v130
	v_sub_f32_e32 v105, v105, v130
	v_sub_f32_e32 v106, v106, v130
	v_sub_f32_e32 v107, v107, v130
	v_sub_f32_e32 v108, v108, v147
	v_sub_f32_e32 v109, v109, v147
	v_sub_f32_e32 v110, v110, v147
	v_sub_f32_e32 v111, v111, v147
	v_sub_f32_e32 v112, v112, v147
	v_sub_f32_e32 v113, v113, v147
	v_sub_f32_e32 v114, v114, v147
	v_sub_f32_e32 v115, v115, v147
	v_sub_f32_e32 v116, v116, v147
	v_sub_f32_e32 v117, v117, v147
	v_sub_f32_e32 v118, v118, v147
	v_sub_f32_e32 v119, v119, v147
	v_sub_f32_e32 v120, v120, v147
	v_sub_f32_e32 v121, v121, v147
	v_sub_f32_e32 v122, v122, v147
	v_sub_f32_e32 v123, v123, v147
	v_mul_f32_e32 v127, v127, v128
	v_pk_mul_f32 v[56:57], v[56:57], v[128:129] op_sel_hi:[1,0]
	v_pk_mul_f32 v[58:59], v[58:59], v[128:129] op_sel_hi:[1,0]
	v_pk_mul_f32 v[52:53], v[52:53], v[128:129] op_sel_hi:[1,0]
	v_pk_mul_f32 v[54:55], v[54:55], v[128:129] op_sel_hi:[1,0]
	v_pk_mul_f32 v[48:49], v[48:49], v[128:129] op_sel_hi:[1,0]
	v_pk_mul_f32 v[50:51], v[50:51], v[128:129] op_sel_hi:[1,0]
	v_pk_mul_f32 v[44:45], v[44:45], v[128:129] op_sel_hi:[1,0]
	v_pk_mul_f32 v[46:47], v[46:47], v[128:129] op_sel_hi:[1,0]
	v_mul_f32_e32 v126, v126, v146
	v_pk_mul_f32 v[40:41], v[40:41], v[146:147] op_sel_hi:[1,0]
	v_pk_mul_f32 v[42:43], v[42:43], v[146:147] op_sel_hi:[1,0]
	v_pk_mul_f32 v[28:29], v[28:29], v[146:147] op_sel_hi:[1,0]
	v_pk_mul_f32 v[30:31], v[30:31], v[146:147] op_sel_hi:[1,0]
	v_pk_mul_f32 v[24:25], v[24:25], v[146:147] op_sel_hi:[1,0]
	v_pk_mul_f32 v[26:27], v[26:27], v[146:147] op_sel_hi:[1,0]
	v_pk_mul_f32 v[20:21], v[20:21], v[146:147] op_sel_hi:[1,0]
	v_pk_mul_f32 v[22:23], v[22:23], v[146:147] op_sel_hi:[1,0]
; template <int CGM>
; __device__ __forceinline__ void pv2(f32x4 (&o)[2][4], const float (&p)[2][4][4], const unsigned char* Vs, int r, int fq) {
;     bf16x8 pb[2][2];
; #pragma unroll
;     for (int cg_ = 0; cg_ < 2; ++cg_) if ((CGM >> cg_) & 1)
; #pragma unroll
;         for (int kc = 0; kc < 2; ++kc) {
;             u32x4 w; w.x = cvt_pk_bf16(p[cg_][2 * kc][0], p[cg_][2 * kc][1]); w.y = cvt_pk_bf16(p[cg_][2 * kc][2], p[cg_][2 * kc][3]);
;             w.z = cvt_pk_bf16(p[cg_][2 * kc + 1][0], p[cg_][2 * kc + 1][1]); w.w = cvt_pk_bf16(p[cg_][2 * kc + 1][2], p[cg_][2 * kc + 1][3]);
;             pb[cg_][kc] = __builtin_bit_cast(bf16x8, w);
;         }
; #pragma unroll
;     for (int df = 0; df < 4; ++df)
; #pragma unroll
;         for (int kc = 0; kc < 2; ++kc) {
;             const int R = prow(df, r);
;             const bf16x8 vf = *(const bf16x8*)(Vs + R * 128 + (((4 * kc + fq) ^ swz(R)) << 4));
;             if (CGM & 1) o[0][df] = __builtin_amdgcn_mfma_f32_16x16x32_bf16(vf, pb[0][kc], o[0][df], 0, 0, 0);
;             if (CGM & 2) o[1][df] = __builtin_amdgcn_mfma_f32_16x16x32_bf16(vf, pb[1][kc], o[1][df], 0, 0, 0);
;         }
; }
; template <int CGM>
; __device__ __forceinline__ void step_int(const bf16x8 (&kf)[4][2], const bf16x8 (&q)[2][2], float farb, const bool (&selq)[2],
;                                          float (&m)[2], float (&l)[2], f32x4 (&o)[2][4], const unsigned char* Vs, int r, int fq) {
;     f32x4 s[2][4]; float mx[2] = {-1e30f, -1e30f};
; #pragma unroll
;     for (int cg_ = 0; cg_ < 2; ++cg_) if ((CGM >> cg_) & 1) { qk(s[cg_], kf, q[cg_], selq[cg_] ? farb - m[cg_] : -1e30f); mx[cg_] = red_max4(max16v(s[cg_])); }
;     if (__any(mx[0] > 0.f || mx[1] > 0.f)) {
; #pragma unroll
;         for (int cg_ = 0; cg_ < 2; ++cg_) if ((CGM >> cg_) & 1) {
;             const float d = fmaxf(mx[cg_], 0.f), sc = __builtin_amdgcn_exp2f(-d); m[cg_] += d; l[cg_] *= sc;
; #pragma unroll
;             for (int df = 0; df < 4; ++df) o[cg_][df] *= sc;
;     ...
;     float p[2][4][4];
; #pragma unroll
;     for (int cg_ = 0; cg_ < 2; ++cg_) if ((CGM >> cg_) & 1) {
;         float rs = 0.f;
; #pragma unroll
;         for (int f = 0; f < 4; ++f)
; #pragma unroll
;             for (int i = 0; i < 4; ++i) { const float pe = __builtin_amdgcn_exp2f(s[cg_][f][i]); p[cg_][f][i] = pe; rs += pe; }
;         l[cg_] += rs;
;     }
;     pv2<CGM>(o, p, Vs, r, fq);
; }
.Lsel_c3_exp:
	v_exp_f32_e32 v92, v92
	v_exp_f32_e32 v93, v93
	v_exp_f32_e32 v94, v94
	v_exp_f32_e32 v95, v95
	v_exp_f32_e32 v96, v96
	v_exp_f32_e32 v97, v97
	v_exp_f32_e32 v98, v98
	v_exp_f32_e32 v99, v99
	v_exp_f32_e32 v100, v100
	v_exp_f32_e32 v101, v101
	v_exp_f32_e32 v102, v102
	v_exp_f32_e32 v103, v103
	v_exp_f32_e32 v104, v104
	v_exp_f32_e32 v105, v105
	v_exp_f32_e32 v106, v106
	v_exp_f32_e32 v107, v107
	v_exp_f32_e32 v108, v108
	v_exp_f32_e32 v109, v109
	v_exp_f32_e32 v110, v110
	v_exp_f32_e32 v111, v111
	v_exp_f32_e32 v112, v112
	v_exp_f32_e32 v113, v113
	v_exp_f32_e32 v114, v114
	v_exp_f32_e32 v115, v115
	v_exp_f32_e32 v116, v116
	v_exp_f32_e32 v117, v117
	v_exp_f32_e32 v118, v118
	v_exp_f32_e32 v119, v119
	v_exp_f32_e32 v120, v120
	v_exp_f32_e32 v121, v121
	v_exp_f32_e32 v122, v122
	v_exp_f32_e32 v123, v123
	v_pk_add_f32 v[130:131], v[92:93], v[94:95]
	v_pk_add_f32 v[130:131], v[130:131], v[96:97]
	v_pk_add_f32 v[130:131], v[130:131], v[98:99]
	v_pk_add_f32 v[130:131], v[130:131], v[100:101]
	v_pk_add_f32 v[130:131], v[130:131], v[102:103]
	v_pk_add_f32 v[130:131], v[130:131], v[104:105]
	v_pk_add_f32 v[130:131], v[130:131], v[106:107]
	v_pk_add_f32 v[146:147], v[108:109], v[110:111]
	v_pk_add_f32 v[146:147], v[146:147], v[112:113]
	v_pk_add_f32 v[146:147], v[146:147], v[114:115]
	v_pk_add_f32 v[146:147], v[146:147], v[116:117]
	v_pk_add_f32 v[146:147], v[146:147], v[118:119]
	v_pk_add_f32 v[146:147], v[146:147], v[120:121]
	v_pk_add_f32 v[146:147], v[146:147], v[122:123]
	v_add_f32_e32 v130, v130, v131
	v_add_f32_e32 v146, v146, v147
	v_add_f32_e32 v127, v127, v130
	v_add_f32_e32 v126, v126, v146
	v_cvt_pk_bf16_f32 v92, v92, v93
	v_cvt_pk_bf16_f32 v93, v94, v95
	v_cvt_pk_bf16_f32 v94, v96, v97
	v_cvt_pk_bf16_f32 v95, v98, v99
	v_cvt_pk_bf16_f32 v96, v100, v101
	v_cvt_pk_bf16_f32 v97, v102, v103
	v_cvt_pk_bf16_f32 v98, v104, v105
	v_cvt_pk_bf16_f32 v99, v106, v107
	v_cvt_pk_bf16_f32 v108, v108, v109
	v_cvt_pk_bf16_f32 v109, v110, v111
	v_cvt_pk_bf16_f32 v110, v112, v113
	v_cvt_pk_bf16_f32 v111, v114, v115
	v_cvt_pk_bf16_f32 v112, v116, v117
	v_cvt_pk_bf16_f32 v113, v118, v119
	v_cvt_pk_bf16_f32 v114, v120, v121
	v_cvt_pk_bf16_f32 v115, v122, v123
	s_nop 0
	s_waitcnt lgkmcnt(7)
	v_mfma_f32_16x16x32_bf16 v[56:59], v[88:91], v[92:95], v[56:59]
	v_mfma_f32_16x16x32_bf16 v[40:43], v[88:91], v[108:111], v[40:43]
	s_waitcnt lgkmcnt(6)
	v_mfma_f32_16x16x32_bf16 v[52:55], v[80:83], v[92:95], v[52:55]
	v_mfma_f32_16x16x32_bf16 v[28:31], v[80:83], v[108:111], v[28:31]
	s_waitcnt lgkmcnt(5)
	v_mfma_f32_16x16x32_bf16 v[48:51], v[72:75], v[92:95], v[48:51]
	v_mfma_f32_16x16x32_bf16 v[24:27], v[72:75], v[108:111], v[24:27]
	s_waitcnt lgkmcnt(4)
	v_mfma_f32_16x16x32_bf16 v[44:47], v[60:63], v[92:95], v[44:47]
	v_mfma_f32_16x16x32_bf16 v[20:23], v[60:63], v[108:111], v[20:23]
	s_waitcnt lgkmcnt(3)
	v_mfma_f32_16x16x32_bf16 v[56:59], v[84:87], v[96:99], v[56:59]
	v_mfma_f32_16x16x32_bf16 v[40:43], v[84:87], v[112:115], v[40:43]
	s_waitcnt lgkmcnt(2)
	v_mfma_f32_16x16x32_bf16 v[52:55], v[76:79], v[96:99], v[52:55]
	v_mfma_f32_16x16x32_bf16 v[28:31], v[76:79], v[112:115], v[28:31]
	s_waitcnt lgkmcnt(1)
	v_mfma_f32_16x16x32_bf16 v[48:51], v[68:71], v[96:99], v[48:51]
	v_mfma_f32_16x16x32_bf16 v[24:27], v[68:71], v[112:115], v[24:27]
	s_waitcnt lgkmcnt(0)
	v_mfma_f32_16x16x32_bf16 v[44:47], v[64:67], v[96:99], v[44:47]
	v_mfma_f32_16x16x32_bf16 v[20:23], v[64:67], v[112:115], v[20:23]
	s_branch .LBB0_2481
.Lsel_c1:
	v_sub_f32_e32 v128, v18, v124
	v_cndmask_b32_e64 v128, v148, v128, s[10:11]
	v_mov_b32_e32 v129, v128
	v_mov_b32_e32 v130, v128
	v_mov_b32_e32 v131, v128
	s_nop 0
	s_waitcnt lgkmcnt(7)
	v_mfma_f32_16x16x32_bf16 v[92:95], v[88:91], v[2:5], v[128:131]
	s_waitcnt lgkmcnt(6)
	v_mfma_f32_16x16x32_bf16 v[96:99], v[80:83], v[2:5], v[128:131]
	s_waitcnt lgkmcnt(5)
	v_mfma_f32_16x16x32_bf16 v[92:95], v[84:87], v[6:9], v[92:95]
	s_waitcnt lgkmcnt(4)
	v_mfma_f32_16x16x32_bf16 v[96:99], v[76:79], v[6:9], v[96:99]
	s_waitcnt lgkmcnt(3)
	v_mfma_f32_16x16x32_bf16 v[100:103], v[72:75], v[2:5], v[128:131]
	s_waitcnt lgkmcnt(2)
	v_mfma_f32_16x16x32_bf16 v[104:107], v[60:63], v[2:5], v[128:131]
	s_waitcnt lgkmcnt(1)
	v_mfma_f32_16x16x32_bf16 v[100:103], v[68:71], v[6:9], v[100:103]
	s_waitcnt lgkmcnt(0)
	v_mfma_f32_16x16x32_bf16 v[104:107], v[64:67], v[6:9], v[104:107]
	ds_read_b128 v[88:91], v143 offset:8192
	ds_read_b128 v[80:83], v143 offset:8704
	ds_read_b128 v[72:75], v143 offset:12288
	ds_read_b128 v[60:63], v143 offset:12800
	ds_read_b128 v[84:87], v142 offset:8192
	ds_read_b128 v[76:79], v142 offset:8704
	ds_read_b128 v[68:71], v142 offset:12288
	ds_read_b128 v[64:67], v142 offset:12800
	v_max3_f32 v128, v92, v93, v94
	v_max3_f32 v129, v95, v96, v97
	v_max3_f32 v130, v98, v99, v100
	v_max3_f32 v131, v101, v102, v103
	v_max3_f32 v128, v128, v104, v105
	v_max3_f32 v129, v129, v106, v107
	v_max3_f32 v128, v128, v129, v130
	v_max_f32_e32 v128, v128, v131
	v_mov_b32_e32 v129, v128
	s_nop 1
	v_permlane16_swap_b32_e32 v128, v129
	v_max_f32_e32 v128, v128, v129
	v_mov_b32_e32 v129, v128
	s_nop 1
	v_permlane32_swap_b32_e32 v128, v129
	v_max_f32_e32 v128, v128, v129
	v_cmp_lt_f32_e32 vcc, 0, v128
	s_cbranch_vccz .Lsel_c1_exp
	v_max_f32_e32 v130, 0, v128
	v_exp_f32_e64 v128, -v130
	v_add_f32_e32 v124, v124, v130
	v_sub_f32_e32 v92, v92, v130
	v_sub_f32_e32 v93, v93, v130
	v_sub_f32_e32 v94, v94, v130
	v_sub_f32_e32 v95, v95, v130
	v_sub_f32_e32 v96, v96, v130
	v_sub_f32_e32 v97, v97, v130
	v_sub_f32_e32 v98, v98, v130
	v_sub_f32_e32 v99, v99, v130
	v_sub_f32_e32 v100, v100, v130
	v_sub_f32_e32 v101, v101, v130
	v_sub_f32_e32 v102, v102, v130
	v_sub_f32_e32 v103, v103, v130
	v_sub_f32_e32 v104, v104, v130
	v_sub_f32_e32 v105, v105, v130
	v_sub_f32_e32 v106, v106, v130
	v_sub_f32_e32 v107, v107, v130
	v_mul_f32_e32 v127, v127, v128
	v_pk_mul_f32 v[56:57], v[56:57], v[128:129] op_sel_hi:[1,0]
	v_pk_mul_f32 v[58:59], v[58:59], v[128:129] op_sel_hi:[1,0]
	v_pk_mul_f32 v[52:53], v[52:53], v[128:129] op_sel_hi:[1,0]
	v_pk_mul_f32 v[54:55], v[54:55], v[128:129] op_sel_hi:[1,0]
	v_pk_mul_f32 v[48:49], v[48:49], v[128:129] op_sel_hi:[1,0]
	v_pk_mul_f32 v[50:51], v[50:51], v[128:129] op_sel_hi:[1,0]
	v_pk_mul_f32 v[44:45], v[44:45], v[128:129] op_sel_hi:[1,0]
	v_pk_mul_f32 v[46:47], v[46:47], v[128:129] op_sel_hi:[1,0]
; template <int CGM>
; __device__ __forceinline__ void step_int(const bf16x8 (&kf)[4][2], const bf16x8 (&q)[2][2], float farb, const bool (&selq)[2],
;                                          float (&m)[2], float (&l)[2], f32x4 (&o)[2][4], const unsigned char* Vs, int r, int fq) {
;     f32x4 s[2][4]; float mx[2] = {-1e30f, -1e30f};
; #pragma unroll
;     for (int cg_ = 0; cg_ < 2; ++cg_) if ((CGM >> cg_) & 1) { qk(s[cg_], kf, q[cg_], selq[cg_] ? farb - m[cg_] : -1e30f); mx[cg_] = red_max4(max16v(s[cg_])); }
;     if (__any(mx[0] > 0.f || mx[1] > 0.f)) {
; #pragma unroll
;         for (int cg_ = 0; cg_ < 2; ++cg_) if ((CGM >> cg_) & 1) {
;             const float d = fmaxf(mx[cg_], 0.f), sc = __builtin_amdgcn_exp2f(-d); m[cg_] += d; l[cg_] *= sc;
; #pragma unroll
;             for (int df = 0; df < 4; ++df) o[cg_][df] *= sc;
; #pragma unroll
;             for (int f = 0; f < 4; ++f) s[cg_][f] -= d;
;         }
;     }
;     float p[2][4][4];
; #pragma unroll
;     for (int cg_ = 0; cg_ < 2; ++cg_) if ((CGM >> cg_) & 1) {
;         float rs = 0.f;
; #pragma unroll
;         for (int f = 0; f < 4; ++f)
; #pragma unroll
;             for (int i = 0; i < 4; ++i) { const float pe = __builtin_amdgcn_exp2f(s[cg_][f][i]); p[cg_][f][i] = pe; rs += pe; }
;         l[cg_] += rs;
;     }
;     pv2<CGM>(o, p, Vs, r, fq);
; }
.Lsel_c1_exp:
	v_exp_f32_e32 v92, v92
	v_exp_f32_e32 v93, v93
	v_exp_f32_e32 v94, v94
	v_exp_f32_e32 v95, v95
	v_exp_f32_e32 v96, v96
	v_exp_f32_e32 v97, v97
	v_exp_f32_e32 v98, v98
	v_exp_f32_e32 v99, v99
	v_exp_f32_e32 v100, v100
	v_exp_f32_e32 v101, v101
	v_exp_f32_e32 v102, v102
	v_exp_f32_e32 v103, v103
	v_exp_f32_e32 v104, v104
	v_exp_f32_e32 v105, v105
	v_exp_f32_e32 v106, v106
	v_exp_f32_e32 v107, v107
	v_pk_add_f32 v[130:131], v[92:93], v[94:95]
	v_pk_add_f32 v[130:131], v[130:131], v[96:97]
	v_pk_add_f32 v[130:131], v[130:131], v[98:99]
	v_pk_add_f32 v[130:131], v[130:131], v[100:101]
	v_pk_add_f32 v[130:131], v[130:131], v[102:103]
	v_pk_add_f32 v[130:131], v[130:131], v[104:105]
	v_pk_add_f32 v[130:131], v[130:131], v[106:107]
	v_add_f32_e32 v130, v130, v131
	v_add_f32_e32 v127, v127, v130
	v_cvt_pk_bf16_f32 v92, v92, v93
	v_cvt_pk_bf16_f32 v93, v94, v95
	v_cvt_pk_bf16_f32 v94, v96, v97
	v_cvt_pk_bf16_f32 v95, v98, v99
	v_cvt_pk_bf16_f32 v96, v100, v101
	v_cvt_pk_bf16_f32 v97, v102, v103
	v_cvt_pk_bf16_f32 v98, v104, v105
	v_cvt_pk_bf16_f32 v99, v106, v107
	s_nop 0
	s_waitcnt lgkmcnt(7)
	v_mfma_f32_16x16x32_bf16 v[56:59], v[88:91], v[92:95], v[56:59]
	s_waitcnt lgkmcnt(6)
	v_mfma_f32_16x16x32_bf16 v[52:55], v[80:83], v[92:95], v[52:55]
	s_waitcnt lgkmcnt(5)
	v_mfma_f32_16x16x32_bf16 v[48:51], v[72:75], v[92:95], v[48:51]
	s_waitcnt lgkmcnt(4)
	v_mfma_f32_16x16x32_bf16 v[44:47], v[60:63], v[92:95], v[44:47]
	s_waitcnt lgkmcnt(3)
	v_mfma_f32_16x16x32_bf16 v[56:59], v[84:87], v[96:99], v[56:59]
	s_waitcnt lgkmcnt(2)
	v_mfma_f32_16x16x32_bf16 v[52:55], v[76:79], v[96:99], v[52:55]
	s_waitcnt lgkmcnt(1)
	v_mfma_f32_16x16x32_bf16 v[48:51], v[68:71], v[96:99], v[48:51]
	s_waitcnt lgkmcnt(0)
	v_mfma_f32_16x16x32_bf16 v[44:47], v[64:67], v[96:99], v[44:47]
	s_branch .LBB0_2481
.Lsel_c2:
	v_sub_f32_e32 v144, v18, v125
	v_cndmask_b32_e64 v144, v148, v144, s[8:9]
	v_mov_b32_e32 v145, v144
	v_mov_b32_e32 v146, v144
	v_mov_b32_e32 v147, v144
	s_nop 0
	s_waitcnt lgkmcnt(7)
	v_mfma_f32_16x16x32_bf16 v[108:111], v[88:91], v[10:13], v[144:147]
	s_waitcnt lgkmcnt(6)
	v_mfma_f32_16x16x32_bf16 v[112:115], v[80:83], v[10:13], v[144:147]
	s_waitcnt lgkmcnt(5)
	v_mfma_f32_16x16x32_bf16 v[108:111], v[84:87], v[14:17], v[108:111]
	s_waitcnt lgkmcnt(4)
	v_mfma_f32_16x16x32_bf16 v[112:115], v[76:79], v[14:17], v[112:115]
	s_waitcnt lgkmcnt(3)
	v_mfma_f32_16x16x32_bf16 v[116:119], v[72:75], v[10:13], v[144:147]
	s_waitcnt lgkmcnt(2)
	v_mfma_f32_16x16x32_bf16 v[120:123], v[60:63], v[10:13], v[144:147]
	s_waitcnt lgkmcnt(1)
	v_mfma_f32_16x16x32_bf16 v[116:119], v[68:71], v[14:17], v[116:119]
	s_waitcnt lgkmcnt(0)
	v_mfma_f32_16x16x32_bf16 v[120:123], v[64:67], v[14:17], v[120:123]
	ds_read_b128 v[88:91], v143 offset:8192
	ds_read_b128 v[80:83], v143 offset:8704
	ds_read_b128 v[72:75], v143 offset:12288
	ds_read_b128 v[60:63], v143 offset:12800
	ds_read_b128 v[84:87], v142 offset:8192
	ds_read_b128 v[76:79], v142 offset:8704
	ds_read_b128 v[68:71], v142 offset:12288
	ds_read_b128 v[64:67], v142 offset:12800
	v_max3_f32 v144, v108, v109, v110
	v_max3_f32 v145, v111, v112, v113
	v_max3_f32 v146, v114, v115, v116
	v_max3_f32 v147, v117, v118, v119
	v_max3_f32 v144, v144, v120, v121
	v_max3_f32 v145, v145, v122, v123
	v_max3_f32 v144, v144, v145, v146
	v_max_f32_e32 v144, v144, v147
	v_mov_b32_e32 v145, v144
	s_nop 1
	v_permlane16_swap_b32_e32 v144, v145
	v_max_f32_e32 v144, v144, v145
	v_mov_b32_e32 v145, v144
	s_nop 1
	v_permlane32_swap_b32_e32 v144, v145
	v_max_f32_e32 v144, v144, v145
	v_cmp_lt_f32_e32 vcc, 0, v144
	s_cbranch_vccz .Lsel_c2_exp
	v_max_f32_e32 v147, 0, v144
	v_exp_f32_e64 v146, -v147
	v_add_f32_e32 v125, v125, v147
	v_sub_f32_e32 v108, v108, v147
	v_sub_f32_e32 v109, v109, v147
	v_sub_f32_e32 v110, v110, v147
	v_sub_f32_e32 v111, v111, v147
	v_sub_f32_e32 v112, v112, v147
	v_sub_f32_e32 v113, v113, v147
	v_sub_f32_e32 v114, v114, v147
	v_sub_f32_e32 v115, v115, v147
	v_sub_f32_e32 v116, v116, v147
	v_sub_f32_e32 v117, v117, v147
	v_sub_f32_e32 v118, v118, v147
	v_sub_f32_e32 v119, v119, v147
	v_sub_f32_e32 v120, v120, v147
	v_sub_f32_e32 v121, v121, v147
	v_sub_f32_e32 v122, v122, v147
	v_sub_f32_e32 v123, v123, v147
	v_mul_f32_e32 v126, v126, v146
	v_pk_mul_f32 v[40:41], v[40:41], v[146:147] op_sel_hi:[1,0]
	v_pk_mul_f32 v[42:43], v[42:43], v[146:147] op_sel_hi:[1,0]
	v_pk_mul_f32 v[28:29], v[28:29], v[146:147] op_sel_hi:[1,0]
	v_pk_mul_f32 v[30:31], v[30:31], v[146:147] op_sel_hi:[1,0]
	v_pk_mul_f32 v[24:25], v[24:25], v[146:147] op_sel_hi:[1,0]
	v_pk_mul_f32 v[26:27], v[26:27], v[146:147] op_sel_hi:[1,0]
	v_pk_mul_f32 v[20:21], v[20:21], v[146:147] op_sel_hi:[1,0]
	v_pk_mul_f32 v[22:23], v[22:23], v[146:147] op_sel_hi:[1,0]
.Lsel_c2_exp:
	v_exp_f32_e32 v108, v108
	v_exp_f32_e32 v109, v109
	v_exp_f32_e32 v110, v110
	v_exp_f32_e32 v111, v111
	v_exp_f32_e32 v112, v112
	v_exp_f32_e32 v113, v113
	v_exp_f32_e32 v114, v114
	v_exp_f32_e32 v115, v115
	v_exp_f32_e32 v116, v116
	v_exp_f32_e32 v117, v117
	v_exp_f32_e32 v118, v118
	v_exp_f32_e32 v119, v119
	v_exp_f32_e32 v120, v120
	v_exp_f32_e32 v121, v121
	v_exp_f32_e32 v122, v122
	v_exp_f32_e32 v123, v123
	v_pk_add_f32 v[146:147], v[108:109], v[110:111]
	v_pk_add_f32 v[146:147], v[146:147], v[112:113]
	v_pk_add_f32 v[146:147], v[146:147], v[114:115]
	v_pk_add_f32 v[146:147], v[146:147], v[116:117]
	v_pk_add_f32 v[146:147], v[146:147], v[118:119]
	v_pk_add_f32 v[146:147], v[146:147], v[120:121]
	v_pk_add_f32 v[146:147], v[146:147], v[122:123]
	v_add_f32_e32 v146, v146, v147
	v_add_f32_e32 v126, v126, v146
	v_cvt_pk_bf16_f32 v108, v108, v109
	v_cvt_pk_bf16_f32 v109, v110, v111
	v_cvt_pk_bf16_f32 v110, v112, v113
	v_cvt_pk_bf16_f32 v111, v114, v115
	v_cvt_pk_bf16_f32 v112, v116, v117
	v_cvt_pk_bf16_f32 v113, v118, v119
	v_cvt_pk_bf16_f32 v114, v120, v121
	v_cvt_pk_bf16_f32 v115, v122, v123
	s_nop 0
	s_waitcnt lgkmcnt(7)
	v_mfma_f32_16x16x32_bf16 v[40:43], v[88:91], v[108:111], v[40:43]
	s_waitcnt lgkmcnt(6)
	v_mfma_f32_16x16x32_bf16 v[28:31], v[80:83], v[108:111], v[28:31]
	s_waitcnt lgkmcnt(5)
	v_mfma_f32_16x16x32_bf16 v[24:27], v[72:75], v[108:111], v[24:27]
	s_waitcnt lgkmcnt(4)
	v_mfma_f32_16x16x32_bf16 v[20:23], v[60:63], v[108:111], v[20:23]
	s_waitcnt lgkmcnt(3)
	v_mfma_f32_16x16x32_bf16 v[40:43], v[84:87], v[112:115], v[40:43]
	s_waitcnt lgkmcnt(2)
	v_mfma_f32_16x16x32_bf16 v[28:31], v[76:79], v[112:115], v[28:31]
	s_waitcnt lgkmcnt(1)
	v_mfma_f32_16x16x32_bf16 v[24:27], v[68:71], v[112:115], v[24:27]
	s_waitcnt lgkmcnt(0)
	v_mfma_f32_16x16x32_bf16 v[20:23], v[64:67], v[112:115], v[20:23]
	s_branch .LBB0_2481

; template <int CGM>
; __device__ __forceinline__ void step_int(const bf16x8 (&kf)[4][2], const bf16x8 (&q)[2][2], float farb, const bool (&selq)[2],
;                                          float (&m)[2], float (&l)[2], f32x4 (&o)[2][4], const unsigned char* Vs, int r, int fq) {
;     f32x4 s[2][4]; float mx[2] = {-1e30f, -1e30f};
; #pragma unroll
;     for (int cg_ = 0; cg_ < 2; ++cg_) if ((CGM >> cg_) & 1) { qk(s[cg_], kf, q[cg_], selq[cg_] ? farb - m[cg_] : -1e30f); mx[cg_] = red_max4(max16v(s[cg_])); }
;     if (__any(mx[0] > 0.f || mx[1] > 0.f)) {
; #pragma unroll
;         for (int cg_ = 0; cg_ < 2; ++cg_) if ((CGM >> cg_) & 1) {
;             const float d = fmaxf(mx[cg_], 0.f), sc = __builtin_amdgcn_exp2f(-d); m[cg_] += d; l[cg_] *= sc;
; #pragma unroll
;             for (int df = 0; df < 4; ++df) o[cg_][df] *= sc;
; #pragma unroll
;             for (int f = 0; f < 4; ++f) s[cg_][f] -= d;
;         }
;     }
; template <bool SEL> ...
;     ...
;             if (any[0] || any[1]) {
;                 const unsigned char* Ks = lds + OFF_RING + slot * SLOTB; const unsigned char* Vs = Ks + 8192;
;                 bf16x8 kf[4][2]; load_kfrags(kf, Ks, r, fq);
;                 const bool edge = (j >= T - 2) || (wl == 512 && j == T - 8);
;                 if (edge) {
;                     if (any[0] && any[1]) step_edge<3>(kf, q, tq, j * 64, fq, H, btab, wl, selq, m, l, o, Vs, r);
;                     else if (any[0]) step_edge<1>(kf, q, tq, j * 64, fq, H, btab, wl, selq, m, l, o, Vs, r);
;                     else step_edge<2>(kf, q, tq, j * 64, fq, H, btab, wl, selq, m, l, o, Vs, r);
;                 } else {
;                     if (any[0] && any[1]) step_int<3>(kf, q, farb, selq, m, l, o, Vs, r, fq);
;                     else if (any[0]) step_int<1>(kf, q, farb, selq, m, l, o, Vs, r, fq);
;                     else step_int<2>(kf, q, farb, selq, m, l, o, Vs, r, fq);
;                 }
.LBB0_2659:
	s_waitcnt lgkmcnt(7)
	ds_read_b128 v[80:83], v149
	s_waitcnt lgkmcnt(7)
	ds_read_b128 v[72:75], v149 offset:512
	s_waitcnt lgkmcnt(7)
	ds_read_b128 v[76:79], v182
	s_waitcnt lgkmcnt(7)
	ds_read_b128 v[68:71], v182 offset:512
	s_waitcnt lgkmcnt(7)
	ds_read_b128 v[60:63], v149 offset:4096
	s_waitcnt lgkmcnt(7)
	ds_read_b128 v[56:59], v149 offset:4608
	s_waitcnt lgkmcnt(7)
	ds_read_b128 v[64:67], v182 offset:4096
	s_waitcnt lgkmcnt(7)
	ds_read_b128 v[52:55], v182 offset:4608
	s_cmp_ge_i32 s38, s93
	s_cselect_b64 s[6:7], -1, 0
	s_cmp_eq_u32 s29, s4
	s_cselect_b64 s[8:9], -1, 0
	s_or_b64 s[6:7], s[6:7], s[8:9]
	s_andn2_b64 vcc, exec, s[6:7]
	s_mov_b64 s[8:9], -1
	s_cbranch_vccz .LBB0_2664
	s_branch .Lwin_int
	v_sub_f32_e32 v84, v18, v156
	v_mov_b32_e32 v85, v84
	v_mov_b32_e32 v86, v84
	v_mov_b32_e32 v87, v84
	s_waitcnt lgkmcnt(7)
	s_nop 0
	v_mfma_f32_16x16x32_bf16 v[88:91], v[80:83], v[2:5], v[84:87]
	s_waitcnt lgkmcnt(5)
	v_mfma_f32_16x16x32_bf16 v[96:99], v[76:79], v[6:9], v[88:91]
	v_mfma_f32_16x16x32_bf16 v[88:91], v[72:75], v[2:5], v[84:87]
	s_waitcnt lgkmcnt(4)
	v_mfma_f32_16x16x32_bf16 v[92:95], v[68:71], v[6:9], v[88:91]
	s_waitcnt lgkmcnt(3)
	v_mfma_f32_16x16x32_bf16 v[88:91], v[60:63], v[2:5], v[84:87]
	s_waitcnt lgkmcnt(2)
	v_mfma_f32_16x16x32_bf16 v[84:87], v[56:59], v[2:5], v[84:87]
	s_waitcnt lgkmcnt(1)
	v_mfma_f32_16x16x32_bf16 v[88:91], v[64:67], v[6:9], v[88:91]
	s_waitcnt lgkmcnt(0)
	v_mfma_f32_16x16x32_bf16 v[84:87], v[52:55], v[6:9], v[84:87]
	v_sub_f32_e32 v102, v18, v157
	v_mov_b32_e32 v103, v102
	v_mov_b32_e32 v104, v102
	v_mov_b32_e32 v105, v102
	v_max3_f32 v112, v96, v97, v98
	v_max3_f32 v113, v99, v92, v93
	v_mfma_f32_16x16x32_bf16 v[106:109], v[80:83], v[10:13], v[102:105]
	v_max3_f32 v114, v94, v95, v88
	v_max3_f32 v115, v89, v90, v91
	v_mfma_f32_16x16x32_bf16 v[128:131], v[76:79], v[14:17], v[106:109]
	v_max3_f32 v112, v112, v84, v85
	v_max3_f32 v113, v113, v86, v87
	v_mfma_f32_16x16x32_bf16 v[106:109], v[72:75], v[10:13], v[102:105]
	v_max3_f32 v112, v112, v113, v114
	v_max3_f32 v100, v112, v115, v115
	v_mfma_f32_16x16x32_bf16 v[136:139], v[68:71], v[14:17], v[106:109]
	v_mov_b32_e32 v101, v100
	v_mfma_f32_16x16x32_bf16 v[106:109], v[60:63], v[10:13], v[102:105]
	v_mfma_f32_16x16x32_bf16 v[102:105], v[56:59], v[10:13], v[102:105]
	v_permlane16_swap_b32_e32 v100, v101
	v_mfma_f32_16x16x32_bf16 v[112:115], v[64:67], v[14:17], v[106:109]
	v_max_f32_e32 v101, v101, v101
	v_max_f32_e32 v100, v100, v100
	v_max_f32_e32 v100, v100, v101
	v_mfma_f32_16x16x32_bf16 v[104:107], v[52:55], v[14:17], v[102:105]
	v_mov_b32_e32 v101, v100
	s_nop 1
	v_permlane32_swap_b32_e32 v100, v101
	v_max_f32_e32 v101, v101, v101
	v_max_f32_e32 v100, v100, v100
	v_max_f32_e32 v100, v100, v101
	v_max3_f32 v101, v128, v129, v130
	v_max3_f32 v108, v113, v114, v115
	v_max3_f32 v102, v131, v136, v137
	v_max3_f32 v101, v101, v104, v105
	v_max3_f32 v103, v138, v139, v112
	v_max3_f32 v102, v102, v106, v107
	v_max3_f32 v101, v101, v102, v103
	v_max3_f32 v101, v101, v108, v108
	v_mov_b32_e32 v102, v101
	s_nop 1
	v_permlane16_swap_b32_e32 v101, v102
	v_max_f32_e32 v102, v102, v102
	v_max_f32_e32 v101, v101, v101
	v_max_f32_e32 v101, v101, v102
	v_mov_b32_e32 v102, v101
	s_nop 1
	v_permlane32_swap_b32_e32 v101, v102
	v_max_f32_e32 v102, v102, v102
	v_max_f32_e32 v101, v101, v101
	v_max_f32_e32 v120, v101, v102
	v_max_f32_e32 v101, v100, v120
	v_cmp_lt_f32_e32 vcc, 0, v101
	s_cbranch_vccz .LBB0_2662
	v_max_f32_e32 v100, v100, v100
	v_max_f32_e32 v184, 0, v100
	v_max_f32_e32 v120, v120, v120
	v_exp_f32_e64 v122, -v184
	v_max_f32_e32 v185, 0, v120
	v_exp_f32_e64 v120, -v185
	v_sub_f32_e32 v96, v96, v184
	v_mov_b32_e32 v121, v122
	v_pk_mul_f32 v[126:127], v[50:51], v[122:123] op_sel_hi:[1,0]
	v_pk_mul_f32 v[124:125], v[48:49], v[122:123] op_sel_hi:[1,0]
	v_pk_mul_f32 v[118:119], v[42:43], v[122:123] op_sel_hi:[1,0]
	v_pk_mul_f32 v[116:117], v[40:41], v[122:123] op_sel_hi:[1,0]
	v_pk_mul_f32 v[102:103], v[34:35], v[122:123] op_sel_hi:[1,0]
	v_pk_mul_f32 v[100:101], v[32:33], v[122:123] op_sel_hi:[1,0]
	v_pk_mul_f32 v[110:111], v[26:27], v[122:123] op_sel_hi:[1,0]
	v_pk_mul_f32 v[108:109], v[24:25], v[122:123] op_sel_hi:[1,0]
	v_sub_f32_e32 v97, v97, v184
	v_sub_f32_e32 v98, v98, v184
	v_sub_f32_e32 v99, v99, v184
	v_sub_f32_e32 v92, v92, v184
	v_sub_f32_e32 v93, v93, v184
	v_sub_f32_e32 v94, v94, v184
	v_sub_f32_e32 v95, v95, v184
	v_sub_f32_e32 v88, v88, v184
	v_sub_f32_e32 v89, v89, v184
	v_sub_f32_e32 v90, v90, v184
	v_sub_f32_e32 v91, v91, v184
	v_sub_f32_e32 v84, v84, v184
	v_sub_f32_e32 v85, v85, v184
	v_sub_f32_e32 v86, v86, v184
	v_sub_f32_e32 v87, v87, v184
	v_pk_add_f32 v[158:159], v[156:157], v[184:185]
	v_pk_mul_f32 v[160:161], v[154:155], v[120:121]
	v_pk_mul_f32 v[146:147], v[46:47], v[120:121] op_sel_hi:[1,0]
	v_pk_mul_f32 v[144:145], v[44:45], v[120:121] op_sel_hi:[1,0]
	v_pk_mul_f32 v[142:143], v[38:39], v[120:121] op_sel_hi:[1,0]
	v_pk_mul_f32 v[140:141], v[36:37], v[120:121] op_sel_hi:[1,0]
	v_pk_mul_f32 v[134:135], v[30:31], v[120:121] op_sel_hi:[1,0]
	v_pk_mul_f32 v[132:133], v[28:29], v[120:121] op_sel_hi:[1,0]
	v_pk_mul_f32 v[122:123], v[22:23], v[120:121] op_sel_hi:[1,0]
	v_pk_mul_f32 v[120:121], v[20:21], v[120:121] op_sel_hi:[1,0]
	v_sub_f32_e32 v128, v128, v185
	v_sub_f32_e32 v129, v129, v185
	v_sub_f32_e32 v130, v130, v185
	v_sub_f32_e32 v131, v131, v185
	v_sub_f32_e32 v136, v136, v185
	v_sub_f32_e32 v137, v137, v185
	v_sub_f32_e32 v138, v138, v185
	v_sub_f32_e32 v139, v139, v185
	v_sub_f32_e32 v112, v112, v185
	v_sub_f32_e32 v113, v113, v185
	v_sub_f32_e32 v114, v114, v185
	v_sub_f32_e32 v115, v115, v185
	v_sub_f32_e32 v104, v104, v185
	v_sub_f32_e32 v105, v105, v185
	v_sub_f32_e32 v106, v106, v185
	v_sub_f32_e32 v107, v107, v185
	s_branch .LBB0_2663

; template <int CGM> ...
;     float v[2][4][4]; float mnew[2] = {m[0], m[1]};
; #pragma unroll
;     for (int cg_ = 0; cg_ < 2; ++cg_) if ((CGM >> cg_) & 1) {
;         f32x4 s[4]; qk(s, kf, q[cg_], 0.f); logits(v[cg_], s, tq[cg_], key0, 1, fq, H, btab, 0.f, true, wl);
;         float mx = red_max4(max16(v[cg_])); if (!selq[cg_]) mx = -1e30f; mnew[cg_] = fmaxf(m[cg_], mx);
; template <bool SEL> ...
;     ...
;                 const bool edge = (j >= T - 2) || (wl == 512 && j == T - 8);
;                 if (edge) {
;                     if (any[0] && any[1]) step_edge<3>(kf, q, tq, j * 64, fq, H, btab, wl, selq, m, l, o, Vs, r);
;                     else if (any[0]) step_edge<1>(kf, q, tq, j * 64, fq, H, btab, wl, selq, m, l, o, Vs, r);
;                     else step_edge<2>(kf, q, tq, j * 64, fq, H, btab, wl, selq, m, l, o, Vs, r);
;                 } else {
.LBB0_2664:
	s_and_b64 vcc, exec, s[8:9]
	s_cbranch_vccz .LBB0_2733
	s_branch .Lwin_edge
	s_waitcnt lgkmcnt(7)
	v_mfma_f32_16x16x32_bf16 v[84:87], v[80:83], v[2:5], 0
	v_add_u32_e32 v102, s4, v179
	v_min_u32_e32 v101, 0x80, v102
	v_cmp_gt_u32_e32 vcc, s92, v102
	s_waitcnt lgkmcnt(5)
	v_mfma_f32_16x16x32_bf16 v[96:99], v[76:79], v[6:9], v[84:87]
	v_mov_b32_e32 v100, 0xf149f2ca
	v_lshl_add_u32 v103, v101, 6, v177
	v_mov_b32_e32 v101, 0xf149f2ca
	v_mfma_f32_16x16x32_bf16 v[84:87], v[72:75], v[2:5], 0
	s_waitcnt lgkmcnt(4)
	v_mfma_f32_16x16x32_bf16 v[92:95], v[68:71], v[6:9], v[84:87]
	s_waitcnt lgkmcnt(3)
	v_mfma_f32_16x16x32_bf16 v[84:87], v[60:63], v[2:5], 0
	s_waitcnt lgkmcnt(1)
	v_mfma_f32_16x16x32_bf16 v[88:91], v[64:67], v[6:9], v[84:87]
	v_mfma_f32_16x16x32_bf16 v[84:87], v[56:59], v[2:5], 0
	s_waitcnt lgkmcnt(0)
	v_mfma_f32_16x16x32_bf16 v[84:87], v[52:55], v[6:9], v[84:87]
	s_and_saveexec_b64 s[8:9], vcc
	s_cbranch_execz .LBB0_2667
	ds_read_b32 v101, v103
	s_waitcnt lgkmcnt(0)
	v_add_f32_e32 v101, v96, v101

; template <int CGM>
; __device__ __forceinline__ void step_int(const bf16x8 (&kf)[4][2], const bf16x8 (&q)[2][2], float farb, const bool (&selq)[2],
;                                          float (&m)[2], float (&l)[2], f32x4 (&o)[2][4], const unsigned char* Vs, int r, int fq) {
;     f32x4 s[2][4]; float mx[2] = {-1e30f, -1e30f};
; #pragma unroll
;     for (int cg_ = 0; cg_ < 2; ++cg_) if ((CGM >> cg_) & 1) { qk(s[cg_], kf, q[cg_], selq[cg_] ? farb - m[cg_] : -1e30f); mx[cg_] = red_max4(max16v(s[cg_])); }
;     if (__any(mx[0] > 0.f || mx[1] > 0.f)) {
; #pragma unroll
;         for (int cg_ = 0; cg_ < 2; ++cg_) if ((CGM >> cg_) & 1) {
;             const float d = fmaxf(mx[cg_], 0.f), sc = __builtin_amdgcn_exp2f(-d); m[cg_] += d; l[cg_] *= sc;
; #pragma unroll
;             for (int df = 0; df < 4; ++df) o[cg_][df] *= sc;
; #pragma unroll
;             for (int f = 0; f < 4; ++f) s[cg_][f] -= d;
;         }
;     }
.Lwin_int:
	v_sub_f32_e32 v188, v18, v156
	v_sub_f32_e32 v192, v18, v157
	v_mov_b32_e32 v189, v188
	v_mov_b32_e32 v190, v188
	v_mov_b32_e32 v191, v188
	v_mov_b32_e32 v193, v192
	v_mov_b32_e32 v194, v192
	v_mov_b32_e32 v195, v192
	s_waitcnt lgkmcnt(7)
	v_mfma_f32_16x16x32_bf16 v[116:119], v[80:83], v[2:5], v[188:191]
	v_mfma_f32_16x16x32_bf16 v[136:139], v[80:83], v[10:13], v[192:195]
	s_waitcnt lgkmcnt(6)
	v_mfma_f32_16x16x32_bf16 v[120:123], v[72:75], v[2:5], v[188:191]
	v_mfma_f32_16x16x32_bf16 v[140:143], v[72:75], v[10:13], v[192:195]
	s_waitcnt lgkmcnt(5)
	v_mfma_f32_16x16x32_bf16 v[116:119], v[76:79], v[6:9], v[116:119]
	v_mfma_f32_16x16x32_bf16 v[136:139], v[76:79], v[14:17], v[136:139]
	s_waitcnt lgkmcnt(4)
	v_mfma_f32_16x16x32_bf16 v[120:123], v[68:71], v[6:9], v[120:123]
	v_mfma_f32_16x16x32_bf16 v[140:143], v[68:71], v[14:17], v[140:143]
	s_waitcnt lgkmcnt(3)
	v_mfma_f32_16x16x32_bf16 v[124:127], v[60:63], v[2:5], v[188:191]
	v_mfma_f32_16x16x32_bf16 v[144:147], v[60:63], v[10:13], v[192:195]
	s_waitcnt lgkmcnt(2)
	v_mfma_f32_16x16x32_bf16 v[132:135], v[56:59], v[2:5], v[188:191]
	v_mfma_f32_16x16x32_bf16 v[184:187], v[56:59], v[10:13], v[192:195]
	s_waitcnt lgkmcnt(1)
	v_mfma_f32_16x16x32_bf16 v[124:127], v[64:67], v[6:9], v[124:127]
	v_mfma_f32_16x16x32_bf16 v[144:147], v[64:67], v[14:17], v[144:147]
	s_waitcnt lgkmcnt(0)
	v_mfma_f32_16x16x32_bf16 v[132:135], v[52:55], v[6:9], v[132:135]
	v_mfma_f32_16x16x32_bf16 v[184:187], v[52:55], v[14:17], v[184:187]
	ds_read_b128 v[80:83], v149 offset:8192
	ds_read_b128 v[72:75], v149 offset:8704
	ds_read_b128 v[60:63], v149 offset:12288
	ds_read_b128 v[56:59], v149 offset:12800
	ds_read_b128 v[76:79], v182 offset:8192
	ds_read_b128 v[68:71], v182 offset:8704
	ds_read_b128 v[64:67], v182 offset:12288
	ds_read_b128 v[52:55], v182 offset:12800
	v_max3_f32 v188, v116, v117, v118
	v_max3_f32 v189, v119, v120, v121
	v_max3_f32 v190, v122, v123, v124
	v_max3_f32 v191, v125, v126, v127
	v_max3_f32 v192, v136, v137, v138
	v_max3_f32 v193, v139, v140, v141
	v_max3_f32 v194, v142, v143, v144
	v_max3_f32 v195, v145, v146, v147
	v_max3_f32 v188, v188, v132, v133
	v_max3_f32 v189, v189, v134, v135
	v_max3_f32 v192, v192, v184, v185
	v_max3_f32 v193, v193, v186, v187
	v_max3_f32 v188, v188, v189, v190
	v_max3_f32 v192, v192, v193, v194
	v_max_f32_e32 v188, v188, v191
	v_max_f32_e32 v192, v192, v195
	v_mov_b32_e32 v189, v188
	v_mov_b32_e32 v193, v192
	s_nop 1
	v_permlane16_swap_b32_e32 v188, v189
	v_permlane16_swap_b32_e32 v192, v193
	v_max_f32_e32 v188, v188, v189
	v_max_f32_e32 v192, v192, v193
	v_mov_b32_e32 v189, v188
	v_mov_b32_e32 v193, v192
	s_nop 1
	v_permlane32_swap_b32_e32 v188, v189
	v_permlane32_swap_b32_e32 v192, v193
	v_max_f32_e32 v188, v188, v189
	v_max_f32_e32 v192, v192, v193
	v_max_f32_e32 v189, v188, v192
	v_cmp_lt_f32_e32 vcc, 0, v189
	s_cbranch_vccz .Lwin_int_exp
	v_max_f32_e32 v190, 0, v188
	v_max_f32_e32 v195, 0, v192
	v_exp_f32_e64 v188, -v190
	v_exp_f32_e64 v194, -v195
	v_add_f32_e32 v156, v156, v190
	v_add_f32_e32 v157, v157, v195
	v_sub_f32_e32 v116, v116, v190
	v_sub_f32_e32 v117, v117, v190
	v_sub_f32_e32 v118, v118, v190
	v_sub_f32_e32 v119, v119, v190
	v_sub_f32_e32 v120, v120, v190
	v_sub_f32_e32 v121, v121, v190
	v_sub_f32_e32 v122, v122, v190
	v_sub_f32_e32 v123, v123, v190
	v_sub_f32_e32 v124, v124, v190
	v_sub_f32_e32 v125, v125, v190
	v_sub_f32_e32 v126, v126, v190
	v_sub_f32_e32 v127, v127, v190
	v_sub_f32_e32 v132, v132, v190
	v_sub_f32_e32 v133, v133, v190
	v_sub_f32_e32 v134, v134, v190
	v_sub_f32_e32 v135, v135, v190
	v_sub_f32_e32 v136, v136, v195
	v_sub_f32_e32 v137, v137, v195
	v_sub_f32_e32 v138, v138, v195
	v_sub_f32_e32 v139, v139, v195
	v_sub_f32_e32 v140, v140, v195
	v_sub_f32_e32 v141, v141, v195
	v_sub_f32_e32 v142, v142, v195
	v_sub_f32_e32 v143, v143, v195
	v_sub_f32_e32 v144, v144, v195
	v_sub_f32_e32 v145, v145, v195
	v_sub_f32_e32 v146, v146, v195
	v_sub_f32_e32 v147, v147, v195
	v_sub_f32_e32 v184, v184, v195
	v_sub_f32_e32 v185, v185, v195
	v_sub_f32_e32 v186, v186, v195
	v_sub_f32_e32 v187, v187, v195
	v_mul_f32_e32 v155, v155, v188
	v_pk_mul_f32 v[48:49], v[48:49], v[188:189] op_sel_hi:[1,0]
	v_pk_mul_f32 v[50:51], v[50:51], v[188:189] op_sel_hi:[1,0]
	v_pk_mul_f32 v[40:41], v[40:41], v[188:189] op_sel_hi:[1,0]
	v_pk_mul_f32 v[42:43], v[42:43], v[188:189] op_sel_hi:[1,0]
	v_pk_mul_f32 v[32:33], v[32:33], v[188:189] op_sel_hi:[1,0]
	v_pk_mul_f32 v[34:35], v[34:35], v[188:189] op_sel_hi:[1,0]
	v_pk_mul_f32 v[24:25], v[24:25], v[188:189] op_sel_hi:[1,0]
	v_pk_mul_f32 v[26:27], v[26:27], v[188:189] op_sel_hi:[1,0]
	v_mul_f32_e32 v154, v154, v194
	v_pk_mul_f32 v[44:45], v[44:45], v[194:195] op_sel_hi:[1,0]
	v_pk_mul_f32 v[46:47], v[46:47], v[194:195] op_sel_hi:[1,0]
	v_pk_mul_f32 v[36:37], v[36:37], v[194:195] op_sel_hi:[1,0]
	v_pk_mul_f32 v[38:39], v[38:39], v[194:195] op_sel_hi:[1,0]
	v_pk_mul_f32 v[28:29], v[28:29], v[194:195] op_sel_hi:[1,0]
	v_pk_mul_f32 v[30:31], v[30:31], v[194:195] op_sel_hi:[1,0]
	v_pk_mul_f32 v[20:21], v[20:21], v[194:195] op_sel_hi:[1,0]
	v_pk_mul_f32 v[22:23], v[22:23], v[194:195] op_sel_hi:[1,0]
; template <int CGM> ...
;     float v[2][4][4]; float mnew[2] = {m[0], m[1]};
; #pragma unroll
;     for (int cg_ = 0; cg_ < 2; ++cg_) if ((CGM >> cg_) & 1) {
;         f32x4 s[4]; qk(s, kf, q[cg_], 0.f); logits(v[cg_], s, tq[cg_], key0, 1, fq, H, btab, 0.f, true, wl);
;         float mx = red_max4(max16(v[cg_])); if (!selq[cg_]) mx = -1e30f; mnew[cg_] = fmaxf(m[cg_], mx);
; template <int CGM>
; __device__ __forceinline__ void step_int(const bf16x8 (&kf)[4][2], const bf16x8 (&q)[2][2], float farb, const bool (&selq)[2],
;                                          float (&m)[2], float (&l)[2], f32x4 (&o)[2][4], const unsigned char* Vs, int r, int fq) {
;     ...
;     float p[2][4][4];
; #pragma unroll
;     for (int cg_ = 0; cg_ < 2; ++cg_) if ((CGM >> cg_) & 1) {
;         float rs = 0.f;
; #pragma unroll
;         for (int f = 0; f < 4; ++f)
; #pragma unroll
;             for (int i = 0; i < 4; ++i) { const float pe = __builtin_amdgcn_exp2f(s[cg_][f][i]); p[cg_][f][i] = pe; rs += pe; }
;         l[cg_] += rs;
;     }
;     pv2<CGM>(o, p, Vs, r, fq);
; }
.Lwin_int_exp:
	v_exp_f32_e32 v116, v116
	v_exp_f32_e32 v117, v117
	v_exp_f32_e32 v118, v118
	v_exp_f32_e32 v119, v119
	v_exp_f32_e32 v120, v120
	v_exp_f32_e32 v121, v121
	v_exp_f32_e32 v122, v122
	v_exp_f32_e32 v123, v123
	v_exp_f32_e32 v124, v124
	v_exp_f32_e32 v125, v125
	v_exp_f32_e32 v126, v126
	v_exp_f32_e32 v127, v127
	v_exp_f32_e32 v132, v132
	v_exp_f32_e32 v133, v133
	v_exp_f32_e32 v134, v134
	v_exp_f32_e32 v135, v135
	v_exp_f32_e32 v136, v136
	v_exp_f32_e32 v137, v137
	v_exp_f32_e32 v138, v138
	v_exp_f32_e32 v139, v139
	v_exp_f32_e32 v140, v140
	v_exp_f32_e32 v141, v141
	v_exp_f32_e32 v142, v142
	v_exp_f32_e32 v143, v143
	v_exp_f32_e32 v144, v144
	v_exp_f32_e32 v145, v145
	v_exp_f32_e32 v146, v146
	v_exp_f32_e32 v147, v147
	v_exp_f32_e32 v184, v184
	v_exp_f32_e32 v185, v185
	v_exp_f32_e32 v186, v186
	v_exp_f32_e32 v187, v187
	v_pk_add_f32 v[190:191], v[116:117], v[118:119]
	v_pk_add_f32 v[190:191], v[190:191], v[120:121]
	v_pk_add_f32 v[190:191], v[190:191], v[122:123]
	v_pk_add_f32 v[190:191], v[190:191], v[124:125]
	v_pk_add_f32 v[190:191], v[190:191], v[126:127]
	v_pk_add_f32 v[190:191], v[190:191], v[132:133]
	v_pk_add_f32 v[190:191], v[190:191], v[134:135]
	v_pk_add_f32 v[194:195], v[136:137], v[138:139]
	v_pk_add_f32 v[194:195], v[194:195], v[140:141]
	v_pk_add_f32 v[194:195], v[194:195], v[142:143]
	v_pk_add_f32 v[194:195], v[194:195], v[144:145]
	v_pk_add_f32 v[194:195], v[194:195], v[146:147]
	v_pk_add_f32 v[194:195], v[194:195], v[184:185]
	v_pk_add_f32 v[194:195], v[194:195], v[186:187]
	v_add_f32_e32 v190, v190, v191
	v_add_f32_e32 v194, v194, v195
	v_add_f32_e32 v129, v155, v190
	v_add_f32_e32 v128, v154, v194
	v_cvt_pk_bf16_f32 v116, v116, v117
	v_cvt_pk_bf16_f32 v117, v118, v119
	v_cvt_pk_bf16_f32 v118, v120, v121
	v_cvt_pk_bf16_f32 v119, v122, v123
	v_cvt_pk_bf16_f32 v120, v124, v125
	v_cvt_pk_bf16_f32 v121, v126, v127
	v_cvt_pk_bf16_f32 v122, v132, v133
	v_cvt_pk_bf16_f32 v123, v134, v135
	v_cvt_pk_bf16_f32 v136, v136, v137
	v_cvt_pk_bf16_f32 v137, v138, v139
	v_cvt_pk_bf16_f32 v138, v140, v141
	v_cvt_pk_bf16_f32 v139, v142, v143
	v_cvt_pk_bf16_f32 v140, v144, v145
	v_cvt_pk_bf16_f32 v141, v146, v147
	v_cvt_pk_bf16_f32 v142, v184, v185
	v_cvt_pk_bf16_f32 v143, v186, v187
	v_mov_b64_e32 v[158:159], v[156:157]
	s_nop 0
	s_waitcnt lgkmcnt(7)
	v_mfma_f32_16x16x32_bf16 v[48:51], v[80:83], v[116:119], v[48:51]
	v_mfma_f32_16x16x32_bf16 v[44:47], v[80:83], v[136:139], v[44:47]
	s_waitcnt lgkmcnt(6)
	v_mfma_f32_16x16x32_bf16 v[40:43], v[72:75], v[116:119], v[40:43]
	v_mfma_f32_16x16x32_bf16 v[36:39], v[72:75], v[136:139], v[36:39]
	s_waitcnt lgkmcnt(5)
	v_mfma_f32_16x16x32_bf16 v[32:35], v[60:63], v[116:119], v[32:35]
	v_mfma_f32_16x16x32_bf16 v[28:31], v[60:63], v[136:139], v[28:31]
	s_waitcnt lgkmcnt(4)
	v_mfma_f32_16x16x32_bf16 v[24:27], v[56:59], v[116:119], v[24:27]
	v_mfma_f32_16x16x32_bf16 v[20:23], v[56:59], v[136:139], v[20:23]
	s_waitcnt lgkmcnt(3)
	v_mfma_f32_16x16x32_bf16 v[92:95], v[76:79], v[120:123], v[48:51]
	v_mfma_f32_16x16x32_bf16 v[84:87], v[76:79], v[140:143], v[44:47]
	s_waitcnt lgkmcnt(2)
	v_mfma_f32_16x16x32_bf16 v[104:107], v[68:71], v[120:123], v[40:43]
	v_mfma_f32_16x16x32_bf16 v[96:99], v[68:71], v[140:143], v[36:39]
	s_waitcnt lgkmcnt(1)
	v_mfma_f32_16x16x32_bf16 v[100:103], v[64:67], v[120:123], v[32:35]
	v_mfma_f32_16x16x32_bf16 v[88:91], v[64:67], v[140:143], v[28:31]
	s_waitcnt lgkmcnt(0)
	v_mfma_f32_16x16x32_bf16 v[112:115], v[52:55], v[120:123], v[24:27]
	v_mfma_f32_16x16x32_bf16 v[108:111], v[52:55], v[140:143], v[20:23]
	s_branch .LBB0_2733
.Lwin_edge:
	v_add_u32_e32 v251, s4, v179
	s_waitcnt lgkmcnt(7)
	v_mfma_f32_16x16x32_bf16 v[116:119], v[80:83], v[2:5], 0
	v_mfma_f32_16x16x32_bf16 v[136:139], v[80:83], v[10:13], 0
	s_waitcnt lgkmcnt(6)
	v_mfma_f32_16x16x32_bf16 v[120:123], v[72:75], v[2:5], 0
	v_mfma_f32_16x16x32_bf16 v[140:143], v[72:75], v[10:13], 0
	s_waitcnt lgkmcnt(5)
	v_mfma_f32_16x16x32_bf16 v[116:119], v[76:79], v[6:9], v[116:119]
	v_mfma_f32_16x16x32_bf16 v[136:139], v[76:79], v[14:17], v[136:139]
	s_waitcnt lgkmcnt(4)
	v_mfma_f32_16x16x32_bf16 v[120:123], v[68:71], v[6:9], v[120:123]
	v_mfma_f32_16x16x32_bf16 v[140:143], v[68:71], v[14:17], v[140:143]
	s_waitcnt lgkmcnt(3)
	v_mfma_f32_16x16x32_bf16 v[124:127], v[60:63], v[2:5], 0
	v_mfma_f32_16x16x32_bf16 v[144:147], v[60:63], v[10:13], 0
	s_waitcnt lgkmcnt(2)
	v_mfma_f32_16x16x32_bf16 v[132:135], v[56:59], v[2:5], 0
	v_mfma_f32_16x16x32_bf16 v[184:187], v[56:59], v[10:13], 0
	s_waitcnt lgkmcnt(1)
	v_mfma_f32_16x16x32_bf16 v[124:127], v[64:67], v[6:9], v[124:127]
	v_mfma_f32_16x16x32_bf16 v[144:147], v[64:67], v[14:17], v[144:147]
	s_waitcnt lgkmcnt(0)
; __device__ __forceinline__ void logits(float (&v)[4][4], const f32x4 (&s)[4], int tq, int kpos0, int kstride, int fq, int H, const float* btab, float farb, bool use_tab, int wl) {
; #pragma unroll
;     for (int f = 0; f < 4; ++f)
; #pragma unroll
;         for (int i = 0; i < 4; ++i) {
;             const int kk = 32 * (f >> 1) + 8 * fq + 4 * (f & 1) + i;
;             const int dist = tq - (kpos0 + kstride * kk);
;             const bool ok = dist >= 0 && dist < wl;
;             const int di = dist < 0 ? 0 : (dist > 128 ? 128 : dist);
;             v[f][i] = ok ? s[f][i] + btab[di * 16 + H] : -1e30f;
;         }
; }
	v_mfma_f32_16x16x32_bf16 v[132:135], v[52:55], v[6:9], v[132:135]
	v_mfma_f32_16x16x32_bf16 v[184:187], v[52:55], v[14:17], v[184:187]
	v_add_u32_e32 v255, 0, v251
	v_min_u32_e32 v255, 0x80, v255
	v_lshl_add_u32 v232, v255, 6, v177
	ds_read_b32 v232, v232
	v_add_u32_e32 v255, -1, v251
	v_min_u32_e32 v255, 0x80, v255
	v_lshl_add_u32 v233, v255, 6, v177
	ds_read_b32 v233, v233
	v_add_u32_e32 v255, -2, v251
	v_min_u32_e32 v255, 0x80, v255
	v_lshl_add_u32 v234, v255, 6, v177
	ds_read_b32 v234, v234
	v_add_u32_e32 v255, -3, v251
	v_min_u32_e32 v255, 0x80, v255
	v_lshl_add_u32 v235, v255, 6, v177
	ds_read_b32 v235, v235
	v_add_u32_e32 v255, -4, v251
	v_min_u32_e32 v255, 0x80, v255
	v_lshl_add_u32 v236, v255, 6, v177
	ds_read_b32 v236, v236
	v_add_u32_e32 v255, -5, v251
	v_min_u32_e32 v255, 0x80, v255
	v_lshl_add_u32 v237, v255, 6, v177
	ds_read_b32 v237, v237
	v_add_u32_e32 v255, -6, v251
	v_min_u32_e32 v255, 0x80, v255
	v_lshl_add_u32 v238, v255, 6, v177
	ds_read_b32 v238, v238
	v_add_u32_e32 v255, -7, v251
	v_min_u32_e32 v255, 0x80, v255
	v_lshl_add_u32 v239, v255, 6, v177
	ds_read_b32 v239, v239
	v_add_u32_e32 v255, 0xffffffe0, v251
	v_min_u32_e32 v255, 0x80, v255
	v_lshl_add_u32 v240, v255, 6, v177
	ds_read_b32 v240, v240
	v_add_u32_e32 v255, 0xffffffdf, v251
	v_min_u32_e32 v255, 0x80, v255
	v_lshl_add_u32 v241, v255, 6, v177
	ds_read_b32 v241, v241
	v_add_u32_e32 v255, 0xffffffde, v251
	v_min_u32_e32 v255, 0x80, v255
	v_lshl_add_u32 v242, v255, 6, v177
	ds_read_b32 v242, v242
	v_add_u32_e32 v255, 0xffffffdd, v251
	v_min_u32_e32 v255, 0x80, v255
	v_lshl_add_u32 v243, v255, 6, v177
	ds_read_b32 v243, v243
	v_add_u32_e32 v255, 0xffffffdc, v251
	v_min_u32_e32 v255, 0x80, v255
	v_lshl_add_u32 v244, v255, 6, v177
	ds_read_b32 v244, v244
	v_add_u32_e32 v255, 0xffffffdb, v251
	v_min_u32_e32 v255, 0x80, v255
	v_lshl_add_u32 v245, v255, 6, v177
	ds_read_b32 v245, v245
	v_add_u32_e32 v255, 0xffffffda, v251
	v_min_u32_e32 v255, 0x80, v255
	v_lshl_add_u32 v246, v255, 6, v177
	ds_read_b32 v246, v246
	v_add_u32_e32 v255, 0xffffffd9, v251
	v_min_u32_e32 v255, 0x80, v255
	v_lshl_add_u32 v247, v255, 6, v177
	ds_read_b32 v247, v247
	v_add_u32_e32 v248, 0, v251
	v_cmp_gt_u32_e64 s[8:9], s92, v248
	v_add_u32_e32 v249, -1, v251
	v_cmp_gt_u32_e64 s[10:11], s92, v249
	v_add_u32_e32 v250, -2, v251
	v_cmp_gt_u32_e64 s[12:13], s92, v250
	s_waitcnt lgkmcnt(15)
	v_add_f32_e32 v116, v116, v232
	v_cndmask_b32_e64 v116, v148, v116, s[8:9]
	v_add_u32_e32 v248, -3, v251
	v_cmp_gt_u32_e64 s[8:9], s92, v248
	s_waitcnt lgkmcnt(14)
	v_add_f32_e32 v117, v117, v233
	v_cndmask_b32_e64 v117, v148, v117, s[10:11]
	v_add_u32_e32 v249, -4, v251
	v_cmp_gt_u32_e64 s[10:11], s92, v249
	s_waitcnt lgkmcnt(13)
	v_add_f32_e32 v118, v118, v234
	v_cndmask_b32_e64 v118, v148, v118, s[12:13]
	v_add_u32_e32 v250, -5, v251
	v_cmp_gt_u32_e64 s[12:13], s92, v250
	s_waitcnt lgkmcnt(12)
	v_add_f32_e32 v119, v119, v235
	v_cndmask_b32_e64 v119, v148, v119, s[8:9]
	v_add_u32_e32 v248, -6, v251
	v_cmp_gt_u32_e64 s[8:9], s92, v248
	s_waitcnt lgkmcnt(11)
	v_add_f32_e32 v120, v120, v236
	v_cndmask_b32_e64 v120, v148, v120, s[10:11]
	v_add_u32_e32 v249, -7, v251
	v_cmp_gt_u32_e64 s[10:11], s92, v249
	s_waitcnt lgkmcnt(10)
	v_add_f32_e32 v121, v121, v237
	v_cndmask_b32_e64 v121, v148, v121, s[12:13]
	v_add_u32_e32 v250, 0xffffffe0, v251
	v_cmp_gt_u32_e64 s[12:13], s92, v250
	s_waitcnt lgkmcnt(9)
	v_add_f32_e32 v122, v122, v238
	v_cndmask_b32_e64 v122, v148, v122, s[8:9]
	v_add_u32_e32 v248, 0xffffffdf, v251
	v_cmp_gt_u32_e64 s[8:9], s92, v248
	s_waitcnt lgkmcnt(8)
	v_add_f32_e32 v123, v123, v239
	v_cndmask_b32_e64 v123, v148, v123, s[10:11]
	v_add_u32_e32 v249, 0xffffffde, v251
	v_cmp_gt_u32_e64 s[10:11], s92, v249
	s_waitcnt lgkmcnt(7)
	v_add_f32_e32 v124, v124, v240
	v_cndmask_b32_e64 v124, v148, v124, s[12:13]
	v_add_u32_e32 v250, 0xffffffdd, v251
	v_cmp_gt_u32_e64 s[12:13], s92, v250
	s_waitcnt lgkmcnt(6)
	v_add_f32_e32 v125, v125, v241
	v_cndmask_b32_e64 v125, v148, v125, s[8:9]
	v_add_u32_e32 v248, 0xffffffdc, v251
	v_cmp_gt_u32_e64 s[8:9], s92, v248
	s_waitcnt lgkmcnt(5)
	v_add_f32_e32 v126, v126, v242
	v_cndmask_b32_e64 v126, v148, v126, s[10:11]
	v_add_u32_e32 v249, 0xffffffdb, v251
	v_cmp_gt_u32_e64 s[10:11], s92, v249
	s_waitcnt lgkmcnt(4)
	v_add_f32_e32 v127, v127, v243
	v_cndmask_b32_e64 v127, v148, v127, s[12:13]
	v_add_u32_e32 v250, 0xffffffda, v251
	v_cmp_gt_u32_e64 s[12:13], s92, v250
	s_waitcnt lgkmcnt(3)
	v_add_f32_e32 v132, v132, v244
	v_cndmask_b32_e64 v132, v148, v132, s[8:9]
	v_add_u32_e32 v248, 0xffffffd9, v251
	v_cmp_gt_u32_e64 s[8:9], s92, v248
	s_waitcnt lgkmcnt(2)
	v_add_f32_e32 v133, v133, v245
	v_cndmask_b32_e64 v133, v148, v133, s[10:11]
	s_waitcnt lgkmcnt(1)
	v_add_f32_e32 v134, v134, v246
	v_cndmask_b32_e64 v134, v148, v134, s[12:13]
	s_waitcnt lgkmcnt(0)
; __device__ __forceinline__ void logits(float (&v)[4][4], const f32x4 (&s)[4], int tq, int kpos0, int kstride, int fq, int H, const float* btab, float farb, bool use_tab, int wl) {
; #pragma unroll
;     for (int f = 0; f < 4; ++f)
; #pragma unroll
;         for (int i = 0; i < 4; ++i) {
;             const int kk = 32 * (f >> 1) + 8 * fq + 4 * (f & 1) + i;
;             const int dist = tq - (kpos0 + kstride * kk);
;             const bool ok = dist >= 0 && dist < wl;
;             const int di = dist < 0 ? 0 : (dist > 128 ? 128 : dist);
;             v[f][i] = ok ? s[f][i] + btab[di * 16 + H] : -1e30f;
;         }
; }
; __device__ __forceinline__ float red_max4(float x) {
;     auto a = __builtin_amdgcn_permlane16_swap(__float_as_uint(x), __float_as_uint(x), false, false); x = fmaxf(__uint_as_float(a[0]), __uint_as_float(a[1]));
;     auto b = __builtin_amdgcn_permlane32_swap(__float_as_uint(x), __float_as_uint(x), false, false); return fmaxf(__uint_as_float(b[0]), __uint_as_float(b[1]));
; }
; template <int CGM> ...
;     ...
;         float mx = red_max4(max16(v[cg_])); if (!selq[cg_]) mx = -1e30f; mnew[cg_] = fmaxf(m[cg_], mx);
;     }
;     if (__any(mnew[0] > m[0] || mnew[1] > m[1])) {
	v_add_f32_e32 v135, v135, v247
	v_cndmask_b32_e64 v135, v148, v135, s[8:9]
	v_add_u32_e32 v255, 4, v251
	v_min_u32_e32 v255, 0x80, v255
	v_lshl_add_u32 v232, v255, 6, v177
	ds_read_b32 v232, v232
	v_add_u32_e32 v255, 3, v251
	v_min_u32_e32 v255, 0x80, v255
	v_lshl_add_u32 v233, v255, 6, v177
	ds_read_b32 v233, v233
	v_add_u32_e32 v255, 2, v251
	v_min_u32_e32 v255, 0x80, v255
	v_lshl_add_u32 v234, v255, 6, v177
	ds_read_b32 v234, v234
	v_add_u32_e32 v255, 1, v251
	v_min_u32_e32 v255, 0x80, v255
	v_lshl_add_u32 v235, v255, 6, v177
	ds_read_b32 v235, v235
	v_add_u32_e32 v255, 0, v251
	v_min_u32_e32 v255, 0x80, v255
	v_lshl_add_u32 v236, v255, 6, v177
	ds_read_b32 v236, v236
	v_add_u32_e32 v255, -1, v251
	v_min_u32_e32 v255, 0x80, v255
	v_lshl_add_u32 v237, v255, 6, v177
	ds_read_b32 v237, v237
	v_add_u32_e32 v255, -2, v251
	v_min_u32_e32 v255, 0x80, v255
	v_lshl_add_u32 v238, v255, 6, v177
	ds_read_b32 v238, v238
	v_add_u32_e32 v255, -3, v251
	v_min_u32_e32 v255, 0x80, v255
	v_lshl_add_u32 v239, v255, 6, v177
	ds_read_b32 v239, v239
	v_add_u32_e32 v255, 0xffffffe4, v251
	v_min_u32_e32 v255, 0x80, v255
	v_lshl_add_u32 v240, v255, 6, v177
	ds_read_b32 v240, v240
	v_add_u32_e32 v255, 0xffffffe3, v251
	v_min_u32_e32 v255, 0x80, v255
	v_lshl_add_u32 v241, v255, 6, v177
	ds_read_b32 v241, v241
	v_add_u32_e32 v255, 0xffffffe2, v251
	v_min_u32_e32 v255, 0x80, v255
	v_lshl_add_u32 v242, v255, 6, v177
	ds_read_b32 v242, v242
	v_add_u32_e32 v255, 0xffffffe1, v251
	v_min_u32_e32 v255, 0x80, v255
	v_lshl_add_u32 v243, v255, 6, v177
	ds_read_b32 v243, v243
	v_add_u32_e32 v255, 0xffffffe0, v251
	v_min_u32_e32 v255, 0x80, v255
	v_lshl_add_u32 v244, v255, 6, v177
	ds_read_b32 v244, v244
	v_add_u32_e32 v255, 0xffffffdf, v251
	v_min_u32_e32 v255, 0x80, v255
	v_lshl_add_u32 v245, v255, 6, v177
	ds_read_b32 v245, v245
	v_add_u32_e32 v255, 0xffffffde, v251
	v_min_u32_e32 v255, 0x80, v255
	v_lshl_add_u32 v246, v255, 6, v177
	ds_read_b32 v246, v246
	v_add_u32_e32 v255, 0xffffffdd, v251
	v_min_u32_e32 v255, 0x80, v255
	v_lshl_add_u32 v247, v255, 6, v177
	ds_read_b32 v247, v247
	v_add_u32_e32 v248, 4, v251
	v_cmp_gt_u32_e64 s[8:9], s92, v248
	v_add_u32_e32 v249, 3, v251
	v_cmp_gt_u32_e64 s[10:11], s92, v249
	v_add_u32_e32 v250, 2, v251
	v_cmp_gt_u32_e64 s[12:13], s92, v250
	s_waitcnt lgkmcnt(15)
	v_add_f32_e32 v136, v136, v232
	v_cndmask_b32_e64 v136, v148, v136, s[8:9]
	v_add_u32_e32 v248, 1, v251
	v_cmp_gt_u32_e64 s[8:9], s92, v248
	s_waitcnt lgkmcnt(14)
	v_add_f32_e32 v137, v137, v233
	v_cndmask_b32_e64 v137, v148, v137, s[10:11]
	v_add_u32_e32 v249, 0, v251
	v_cmp_gt_u32_e64 s[10:11], s92, v249
	s_waitcnt lgkmcnt(13)
	v_add_f32_e32 v138, v138, v234
	v_cndmask_b32_e64 v138, v148, v138, s[12:13]
	v_add_u32_e32 v250, -1, v251
	v_cmp_gt_u32_e64 s[12:13], s92, v250
	s_waitcnt lgkmcnt(12)
	v_add_f32_e32 v139, v139, v235
	v_cndmask_b32_e64 v139, v148, v139, s[8:9]
	v_add_u32_e32 v248, -2, v251
	v_cmp_gt_u32_e64 s[8:9], s92, v248
	s_waitcnt lgkmcnt(11)
	v_add_f32_e32 v140, v140, v236
	v_cndmask_b32_e64 v140, v148, v140, s[10:11]
	v_add_u32_e32 v249, -3, v251
	v_cmp_gt_u32_e64 s[10:11], s92, v249
	s_waitcnt lgkmcnt(10)
	v_add_f32_e32 v141, v141, v237
	v_cndmask_b32_e64 v141, v148, v141, s[12:13]
	v_add_u32_e32 v250, 0xffffffe4, v251
	v_cmp_gt_u32_e64 s[12:13], s92, v250
	s_waitcnt lgkmcnt(9)
	v_add_f32_e32 v142, v142, v238
	v_cndmask_b32_e64 v142, v148, v142, s[8:9]
	v_add_u32_e32 v248, 0xffffffe3, v251
	v_cmp_gt_u32_e64 s[8:9], s92, v248
	s_waitcnt lgkmcnt(8)
	v_add_f32_e32 v143, v143, v239
	v_cndmask_b32_e64 v143, v148, v143, s[10:11]
	v_add_u32_e32 v249, 0xffffffe2, v251
	v_cmp_gt_u32_e64 s[10:11], s92, v249
	s_waitcnt lgkmcnt(7)
	v_add_f32_e32 v144, v144, v240
	v_cndmask_b32_e64 v144, v148, v144, s[12:13]
	v_add_u32_e32 v250, 0xffffffe1, v251
	v_cmp_gt_u32_e64 s[12:13], s92, v250
	s_waitcnt lgkmcnt(6)
	v_add_f32_e32 v145, v145, v241
	v_cndmask_b32_e64 v145, v148, v145, s[8:9]
	v_add_u32_e32 v248, 0xffffffe0, v251
	v_cmp_gt_u32_e64 s[8:9], s92, v248
	s_waitcnt lgkmcnt(5)
	v_add_f32_e32 v146, v146, v242
	v_cndmask_b32_e64 v146, v148, v146, s[10:11]
	v_add_u32_e32 v249, 0xffffffdf, v251
	v_cmp_gt_u32_e64 s[10:11], s92, v249
	s_waitcnt lgkmcnt(4)
	v_add_f32_e32 v147, v147, v243
	v_cndmask_b32_e64 v147, v148, v147, s[12:13]
	v_add_u32_e32 v250, 0xffffffde, v251
	v_cmp_gt_u32_e64 s[12:13], s92, v250
	s_waitcnt lgkmcnt(3)
	v_add_f32_e32 v184, v184, v244
	v_cndmask_b32_e64 v184, v148, v184, s[8:9]
	v_add_u32_e32 v248, 0xffffffdd, v251
	v_cmp_gt_u32_e64 s[8:9], s92, v248
	s_waitcnt lgkmcnt(2)
	v_add_f32_e32 v185, v185, v245
	v_cndmask_b32_e64 v185, v148, v185, s[10:11]
	s_waitcnt lgkmcnt(1)
	v_add_f32_e32 v186, v186, v246
	v_cndmask_b32_e64 v186, v148, v186, s[12:13]
	s_waitcnt lgkmcnt(0)
	v_add_f32_e32 v187, v187, v247
	v_cndmask_b32_e64 v187, v148, v187, s[8:9]
	ds_read_b128 v[80:83], v149 offset:8192
	ds_read_b128 v[72:75], v149 offset:8704
	ds_read_b128 v[60:63], v149 offset:12288
	ds_read_b128 v[56:59], v149 offset:12800
	ds_read_b128 v[76:79], v182 offset:8192
	ds_read_b128 v[68:71], v182 offset:8704
	ds_read_b128 v[64:67], v182 offset:12288
	ds_read_b128 v[52:55], v182 offset:12800
	v_max3_f32 v188, v116, v117, v118
	v_max3_f32 v189, v119, v120, v121
	v_max3_f32 v190, v122, v123, v124
	v_max3_f32 v191, v125, v126, v127
	v_max3_f32 v192, v136, v137, v138
	v_max3_f32 v193, v139, v140, v141
	v_max3_f32 v194, v142, v143, v144
	v_max3_f32 v195, v145, v146, v147
	v_max3_f32 v188, v188, v132, v133
	v_max3_f32 v189, v189, v134, v135
	v_max3_f32 v192, v192, v184, v185
	v_max3_f32 v193, v193, v186, v187
	v_max3_f32 v188, v188, v189, v190
	v_max3_f32 v192, v192, v193, v194
	v_max_f32_e32 v188, v188, v191
	v_max_f32_e32 v192, v192, v195
	v_mov_b32_e32 v189, v188
	v_mov_b32_e32 v193, v192
	s_nop 1
	v_permlane16_swap_b32_e32 v188, v189
	v_permlane16_swap_b32_e32 v192, v193
	v_max_f32_e32 v188, v188, v189
	v_max_f32_e32 v192, v192, v193
	v_mov_b32_e32 v189, v188
	v_mov_b32_e32 v193, v192
	s_nop 1
	v_permlane32_swap_b32_e32 v188, v189
	v_permlane32_swap_b32_e32 v192, v193
	v_max_f32_e32 v188, v188, v189
	v_max_f32_e32 v192, v192, v193
	v_max_f32_e32 v189, v156, v188
	v_max_f32_e32 v193, v157, v192
	v_cmp_gt_f32_e32 vcc, v189, v156
	v_cmp_gt_f32_e64 s[8:9], v193, v157
	s_or_b64 vcc, vcc, s[8:9]
	s_cbranch_vccz .Lwin_edge_nors
; __device__ __forceinline__ unsigned cvt_pk_bf16(float lo, float hi) { unsigned r; asm volatile("v_cvt_pk_bf16_f32 %0, %1, %2" : "=v"(r) : "v"(lo), "v"(hi)); return r; }
; __device__ __forceinline__ int swz(int R) { return (R & 2) | ((R & 8) >> 1); }
; template <int CGM>
; __device__ __forceinline__ void pv2(f32x4 (&o)[2][4], const float (&p)[2][4][4], const unsigned char* Vs, int r, int fq) {
;     bf16x8 pb[2][2];
; #pragma unroll
;     for (int cg_ = 0; cg_ < 2; ++cg_) if ((CGM >> cg_) & 1)
; #pragma unroll
;         for (int kc = 0; kc < 2; ++kc) {
;             u32x4 w; w.x = cvt_pk_bf16(p[cg_][2 * kc][0], p[cg_][2 * kc][1]); w.y = cvt_pk_bf16(p[cg_][2 * kc][2], p[cg_][2 * kc][3]);
;             w.z = cvt_pk_bf16(p[cg_][2 * kc + 1][0], p[cg_][2 * kc + 1][1]); w.w = cvt_pk_bf16(p[cg_][2 * kc + 1][2], p[cg_][2 * kc + 1][3]);
;             pb[cg_][kc] = __builtin_bit_cast(bf16x8, w);
;         }
; #pragma unroll
;     for (int df = 0; df < 4; ++df)
; #pragma unroll
;         for (int kc = 0; kc < 2; ++kc) {
;             const int R = prow(df, r);
;             const bf16x8 vf = *(const bf16x8*)(Vs + R * 128 + (((4 * kc + fq) ^ swz(R)) << 4));
;             if (CGM & 1) o[0][df] = __builtin_amdgcn_mfma_f32_16x16x32_bf16(vf, pb[0][kc], o[0][df], 0, 0, 0);
;             if (CGM & 2) o[1][df] = __builtin_amdgcn_mfma_f32_16x16x32_bf16(vf, pb[1][kc], o[1][df], 0, 0, 0);
;         }
; }
; template <int CGM> ...
;     ...
;     if (__any(mnew[0] > m[0] || mnew[1] > m[1])) {
; #pragma unroll
;         for (int cg_ = 0; cg_ < 2; ++cg_) if ((CGM >> cg_) & 1) {
;             const float sc = __builtin_amdgcn_exp2f(m[cg_] - mnew[cg_]); l[cg_] *= sc; m[cg_] = mnew[cg_];
; #pragma unroll
;             for (int df = 0; df < 4; ++df) o[cg_][df] *= sc;
;         }
;     }
; #pragma unroll
;     for (int cg_ = 0; cg_ < 2; ++cg_) if ((CGM >> cg_) & 1) {
;         const float moff = selq[cg_] ? m[cg_] : 1e30f; float rs = 0.f;
; #pragma unroll
;         for (int f = 0; f < 4; ++f)
; #pragma unroll
;             for (int i = 0; i < 4; ++i) { const float pe = __builtin_amdgcn_exp2f(v[cg_][f][i] - moff); v[cg_][f][i] = pe; rs += pe; }
;         l[cg_] += rs;
;     }
;     pv2<CGM>(o, v, Vs, r, fq);
; }
	v_sub_f32_e32 v188, v156, v189
	v_sub_f32_e32 v194, v157, v193
	v_exp_f32_e32 v188, v188
	v_exp_f32_e32 v194, v194
	v_mov_b32_e32 v156, v189
	v_mov_b32_e32 v157, v193
	v_mul_f32_e32 v155, v155, v188
	v_pk_mul_f32 v[48:49], v[48:49], v[188:189] op_sel_hi:[1,0]
	v_pk_mul_f32 v[50:51], v[50:51], v[188:189] op_sel_hi:[1,0]
	v_pk_mul_f32 v[40:41], v[40:41], v[188:189] op_sel_hi:[1,0]
	v_pk_mul_f32 v[42:43], v[42:43], v[188:189] op_sel_hi:[1,0]
	v_pk_mul_f32 v[32:33], v[32:33], v[188:189] op_sel_hi:[1,0]
	v_pk_mul_f32 v[34:35], v[34:35], v[188:189] op_sel_hi:[1,0]
	v_pk_mul_f32 v[24:25], v[24:25], v[188:189] op_sel_hi:[1,0]
	v_pk_mul_f32 v[26:27], v[26:27], v[188:189] op_sel_hi:[1,0]
	v_mul_f32_e32 v154, v154, v194
	v_pk_mul_f32 v[44:45], v[44:45], v[194:195] op_sel_hi:[1,0]
	v_pk_mul_f32 v[46:47], v[46:47], v[194:195] op_sel_hi:[1,0]
	v_pk_mul_f32 v[36:37], v[36:37], v[194:195] op_sel_hi:[1,0]
	v_pk_mul_f32 v[38:39], v[38:39], v[194:195] op_sel_hi:[1,0]
	v_pk_mul_f32 v[28:29], v[28:29], v[194:195] op_sel_hi:[1,0]
	v_pk_mul_f32 v[30:31], v[30:31], v[194:195] op_sel_hi:[1,0]
	v_pk_mul_f32 v[20:21], v[20:21], v[194:195] op_sel_hi:[1,0]
	v_pk_mul_f32 v[22:23], v[22:23], v[194:195] op_sel_hi:[1,0]
.Lwin_edge_nors:
	v_mov_b32_e32 v190, v156
	v_mov_b32_e32 v195, v157
	v_sub_f32_e32 v116, v116, v190
	v_sub_f32_e32 v117, v117, v190
	v_sub_f32_e32 v118, v118, v190
	v_sub_f32_e32 v119, v119, v190
	v_sub_f32_e32 v120, v120, v190
	v_sub_f32_e32 v121, v121, v190
	v_sub_f32_e32 v122, v122, v190
	v_sub_f32_e32 v123, v123, v190
	v_sub_f32_e32 v124, v124, v190
	v_sub_f32_e32 v125, v125, v190
	v_sub_f32_e32 v126, v126, v190
	v_sub_f32_e32 v127, v127, v190
	v_sub_f32_e32 v132, v132, v190
	v_sub_f32_e32 v133, v133, v190
	v_sub_f32_e32 v134, v134, v190
	v_sub_f32_e32 v135, v135, v190
	v_sub_f32_e32 v136, v136, v195
	v_sub_f32_e32 v137, v137, v195
	v_sub_f32_e32 v138, v138, v195
	v_sub_f32_e32 v139, v139, v195
	v_sub_f32_e32 v140, v140, v195
	v_sub_f32_e32 v141, v141, v195
	v_sub_f32_e32 v142, v142, v195
	v_sub_f32_e32 v143, v143, v195
	v_sub_f32_e32 v144, v144, v195
	v_sub_f32_e32 v145, v145, v195
	v_sub_f32_e32 v146, v146, v195
	v_sub_f32_e32 v147, v147, v195
	v_sub_f32_e32 v184, v184, v195
	v_sub_f32_e32 v185, v185, v195
	v_sub_f32_e32 v186, v186, v195
	v_sub_f32_e32 v187, v187, v195
	v_exp_f32_e32 v116, v116
	v_exp_f32_e32 v117, v117
	v_exp_f32_e32 v118, v118
	v_exp_f32_e32 v119, v119
	v_exp_f32_e32 v120, v120
	v_exp_f32_e32 v121, v121
	v_exp_f32_e32 v122, v122
	v_exp_f32_e32 v123, v123
	v_exp_f32_e32 v124, v124
	v_exp_f32_e32 v125, v125
	v_exp_f32_e32 v126, v126
	v_exp_f32_e32 v127, v127
	v_exp_f32_e32 v132, v132
	v_exp_f32_e32 v133, v133
	v_exp_f32_e32 v134, v134
	v_exp_f32_e32 v135, v135
	v_exp_f32_e32 v136, v136
	v_exp_f32_e32 v137, v137
	v_exp_f32_e32 v138, v138
	v_exp_f32_e32 v139, v139
	v_exp_f32_e32 v140, v140
	v_exp_f32_e32 v141, v141
	v_exp_f32_e32 v142, v142
	v_exp_f32_e32 v143, v143
	v_exp_f32_e32 v144, v144
	v_exp_f32_e32 v145, v145
	v_exp_f32_e32 v146, v146
	v_exp_f32_e32 v147, v147
	v_exp_f32_e32 v184, v184
	v_exp_f32_e32 v185, v185
	v_exp_f32_e32 v186, v186
	v_exp_f32_e32 v187, v187
	v_pk_add_f32 v[190:191], v[116:117], v[118:119]
	v_pk_add_f32 v[190:191], v[190:191], v[120:121]
	v_pk_add_f32 v[190:191], v[190:191], v[122:123]
	v_pk_add_f32 v[190:191], v[190:191], v[124:125]
	v_pk_add_f32 v[190:191], v[190:191], v[126:127]
	v_pk_add_f32 v[190:191], v[190:191], v[132:133]
	v_pk_add_f32 v[190:191], v[190:191], v[134:135]
	v_pk_add_f32 v[194:195], v[136:137], v[138:139]
	v_pk_add_f32 v[194:195], v[194:195], v[140:141]
	v_pk_add_f32 v[194:195], v[194:195], v[142:143]
	v_pk_add_f32 v[194:195], v[194:195], v[144:145]
	v_pk_add_f32 v[194:195], v[194:195], v[146:147]
	v_pk_add_f32 v[194:195], v[194:195], v[184:185]
	v_pk_add_f32 v[194:195], v[194:195], v[186:187]
	v_add_f32_e32 v190, v190, v191
	v_add_f32_e32 v194, v194, v195
	v_add_f32_e32 v129, v155, v190
	v_add_f32_e32 v128, v154, v194
	v_cvt_pk_bf16_f32 v116, v116, v117
	v_cvt_pk_bf16_f32 v117, v118, v119
	v_cvt_pk_bf16_f32 v118, v120, v121
	v_cvt_pk_bf16_f32 v119, v122, v123
	v_cvt_pk_bf16_f32 v120, v124, v125
	v_cvt_pk_bf16_f32 v121, v126, v127
	v_cvt_pk_bf16_f32 v122, v132, v133
	v_cvt_pk_bf16_f32 v123, v134, v135
	v_cvt_pk_bf16_f32 v136, v136, v137
	v_cvt_pk_bf16_f32 v137, v138, v139
	v_cvt_pk_bf16_f32 v138, v140, v141
	v_cvt_pk_bf16_f32 v139, v142, v143
	v_cvt_pk_bf16_f32 v140, v144, v145
	v_cvt_pk_bf16_f32 v141, v146, v147
	v_cvt_pk_bf16_f32 v142, v184, v185
	v_cvt_pk_bf16_f32 v143, v186, v187
	v_mov_b64_e32 v[158:159], v[156:157]
	s_nop 0
	s_waitcnt lgkmcnt(7)
	v_mfma_f32_16x16x32_bf16 v[48:51], v[80:83], v[116:119], v[48:51]
	v_mfma_f32_16x16x32_bf16 v[44:47], v[80:83], v[136:139], v[44:47]
	s_waitcnt lgkmcnt(6)
	v_mfma_f32_16x16x32_bf16 v[40:43], v[72:75], v[116:119], v[40:43]
	v_mfma_f32_16x16x32_bf16 v[36:39], v[72:75], v[136:139], v[36:39]
	s_waitcnt lgkmcnt(5)
	v_mfma_f32_16x16x32_bf16 v[32:35], v[60:63], v[116:119], v[32:35]
	v_mfma_f32_16x16x32_bf16 v[28:31], v[60:63], v[136:139], v[28:31]
	s_waitcnt lgkmcnt(4)
	v_mfma_f32_16x16x32_bf16 v[24:27], v[56:59], v[116:119], v[24:27]
	v_mfma_f32_16x16x32_bf16 v[20:23], v[56:59], v[136:139], v[20:23]
	s_waitcnt lgkmcnt(3)
	v_mfma_f32_16x16x32_bf16 v[92:95], v[76:79], v[120:123], v[48:51]
	v_mfma_f32_16x16x32_bf16 v[84:87], v[76:79], v[140:143], v[44:47]
	s_waitcnt lgkmcnt(2)
	v_mfma_f32_16x16x32_bf16 v[104:107], v[68:71], v[120:123], v[40:43]
	v_mfma_f32_16x16x32_bf16 v[96:99], v[68:71], v[140:143], v[36:39]
	s_waitcnt lgkmcnt(1)
	v_mfma_f32_16x16x32_bf16 v[100:103], v[64:67], v[120:123], v[32:35]
	v_mfma_f32_16x16x32_bf16 v[88:91], v[64:67], v[140:143], v[28:31]
	s_waitcnt lgkmcnt(0)
	v_mfma_f32_16x16x32_bf16 v[112:115], v[52:55], v[120:123], v[24:27]
	v_mfma_f32_16x16x32_bf16 v[108:111], v[52:55], v[140:143], v[20:23]
	s_branch .LBB0_2733

; __global__ void __launch_bounds__(512, 2) fwd_megakernel(Params p) {
	.amdhsa_kernel _Z14fwd_megakernel6Params
		.amdhsa_group_segment_fixed_size 0
		.amdhsa_private_segment_fixed_size 0
		.amdhsa_kernarg_size 504
		.amdhsa_user_sgpr_count 2
		.amdhsa_user_sgpr_dispatch_ptr 0
		.amdhsa_user_sgpr_queue_ptr 0
		.amdhsa_user_sgpr_kernarg_segment_ptr 1
		.amdhsa_user_sgpr_dispatch_id 0
		.amdhsa_user_sgpr_kernarg_preload_length 0
		.amdhsa_user_sgpr_kernarg_preload_offset 0
		.amdhsa_user_sgpr_private_segment_size 0
		.amdhsa_uses_dynamic_stack 0
		.amdhsa_enable_private_segment 0
		.amdhsa_system_sgpr_workgroup_id_x 1
		.amdhsa_system_sgpr_workgroup_id_y 0
		.amdhsa_system_sgpr_workgroup_id_z 0
		.amdhsa_system_sgpr_workgroup_info 0
		.amdhsa_system_vgpr_workitem_id 2
		.amdhsa_next_free_vgpr 256
		.amdhsa_next_free_sgpr 100
		.amdhsa_accum_offset 256
		.amdhsa_reserve_vcc 1
		.amdhsa_float_round_mode_32 0
		.amdhsa_float_round_mode_16_64 0
		.amdhsa_float_denorm_mode_32 3
		.amdhsa_float_denorm_mode_16_64 3
		.amdhsa_dx10_clamp 1
		.amdhsa_ieee_mode 1
		.amdhsa_fp16_overflow 0
		.amdhsa_tg_split 0
		.amdhsa_exception_fp_ieee_invalid_op 0
		.amdhsa_exception_fp_denorm_src 0
		.amdhsa_exception_fp_ieee_div_zero 0
		.amdhsa_exception_fp_ieee_overflow 0
		.amdhsa_exception_fp_ieee_underflow 0
		.amdhsa_exception_fp_ieee_inexact 0
		.amdhsa_exception_int_div_zero 0
	.end_amdhsa_kernel

; __global__ void __launch_bounds__(512, 2) fwd_megakernel(Params p) {
amdhsa.kernels:
  - .agpr_count:     0
    .args:
      - .offset:         0
        .size:           248
        .value_kind:     by_value
      - .offset:         248
        .size:           4
        .value_kind:     hidden_block_count_x
      - .offset:         252
        .size:           4
        .value_kind:     hidden_block_count_y
      - .offset:         256
        .size:           4
        .value_kind:     hidden_block_count_z
      - .offset:         260
        .size:           2
        .value_kind:     hidden_group_size_x
      - .offset:         262
        .size:           2
        .value_kind:     hidden_group_size_y
      - .offset:         264
        .size:           2
        .value_kind:     hidden_group_size_z
      - .offset:         266
        .size:           2
        .value_kind:     hidden_remainder_x
      - .offset:         268
        .size:           2
        .value_kind:     hidden_remainder_y
      - .offset:         270
        .size:           2
        .value_kind:     hidden_remainder_z
      - .offset:         288
        .size:           8
        .value_kind:     hidden_global_offset_x
      - .offset:         296
        .size:           8
        .value_kind:     hidden_global_offset_y
      - .offset:         304
        .size:           8
        .value_kind:     hidden_global_offset_z
      - .offset:         312
        .size:           2
        .value_kind:     hidden_grid_dims
      - .offset:         336
        .size:           8
        .value_kind:     hidden_multigrid_sync_arg
      - .offset:         368
        .size:           4
        .value_kind:     hidden_dynamic_lds_size
    .group_segment_fixed_size: 0
    .kernarg_segment_align: 8
    .kernarg_segment_size: 504
    .language:       OpenCL C
    .language_version:
      - 2
      - 0
    .max_flat_workgroup_size: 512
    .name:           _Z14fwd_megakernel6Params
    .private_segment_fixed_size: 0
    .sgpr_count:     106
    .sgpr_spill_count: 72
    .symbol:         _Z14fwd_megakernel6Params.kd
    .uniform_work_group_size: 1
    .uses_dynamic_stack: false
    .vgpr_count:     256
    .vgpr_spill_count: 0
    .wavefront_size: 64
